# MLA attention interior loop rewritten as a software pipeline over 32-key half tiles (QK MFMAs under the previous half's exp/pack); SwiGLU epilogue hand-scheduled with loads and g*u hoisted above the e
# speedup vs baseline: 1.0120x; 1.0120x over previous
; #define LAS __attribute__((address_space(3)))
; __device__ __forceinline__ int crow(int r, int hi) { return (r & 3) + 8 * (r >> 2) + 4 * hi; }
; __device__ __forceinline__ float ex2(float x) { return __builtin_amdgcn_exp2f(x); }
; #define MFMA32(a, b, c) __builtin_amdgcn_mfma_f32_32x32x16_bf16((a), (b), (c), 0, 0, 0)
; template <bool MASK> __device__ __forceinline__ void sm_tile(f32x16& p0, f32x16& p1, float& mrun, float& lrun, f32x16& o0, f32x16& o1, LAS float* wsf, int kv0, int qpos, int q32, int hi) {
;     ...
;     float rm = fmaxf(p0[0], p1[0]);
; #pragma unroll
;     for (int r = 1; r < 16; ++r) rm = fmaxf(rm, fmaxf(p0[r], p1[r]));
;     rm = fmaxf(rm, xhalf(rm, hi));
;     if (__any(rm > mrun + 8.0f)) {
;         const float mnew = fmaxf(mrun, rm), alpha = ex2(mrun - mnew); mrun = mnew; lrun *= alpha;
;         if (hi == 0) wsf[q32] = alpha;
;         __builtin_amdgcn_fence(__ATOMIC_RELEASE, "wavefront"); asm volatile("s_waitcnt lgkmcnt(0)" ::: "memory");
; #pragma unroll
;         for (int r = 0; r < 16; ++r) { const float al = wsf[crow(r, hi)]; o0[r] *= al; o1[r] *= al; }
;         asm volatile("" ::: "memory");
;     }
; template <bool MASK> __device__ __forceinline__ void sm_iter(int var, SmState& st, const bf16x8 (&qr)[6], const LAS unsigned char* kb, const LAS unsigned char* vb, LAS float* wsf, int kv0, int qpos, int q32, int hi) {
;     ...
;     for (int d0 = 0; d0 < ND; ++d0) { kf[2 * d0] = *(const LAS bf16x8*)(kb + d0 * 32); kf[2 * d0 + 1] = *(const LAS bf16x8*)(kb + 32 * KP + d0 * 32); }
;     __builtin_amdgcn_sched_barrier(0);
; #pragma unroll
;     for (int d0 = 0; d0 < ND; ++d0) { p0 = MFMA32(kf[2 * d0], qr[d0], p0); p1 = MFMA32(kf[2 * d0 + 1], qr[d0], p1); }
; #pragma unroll
;     for (int j = 0; j < 4; ++j) { vlo[2 * j] = *(const LAS s16x4*)(vb + j * 32); vhh[2 * j] = *(const LAS s16x4*)(vb + j * 32 + 16);
;         vlo[2 * j + 1] = *(const LAS s16x4*)(vb + 32 * VP + j * 32); vhh[2 * j + 1] = *(const LAS s16x4*)(vb + 32 * VP + j * 32 + 16); }
;     __builtin_amdgcn_sched_barrier(0);
;     if (var != 1) sm_tile<MASK>(p0, p1, st.mrun, st.lrun, st.o0, st.o1, wsf, kv0, qpos, q32, hi);
.LBB0_48:
	v_lshl_add_u64 v[2:3], s[22:23], 0, v[166:167]
	v_add_co_u32_e32 v4, vcc, 0x104a0000, v2
	v_lshl_add_u64 v[10:11], s[22:23], 0, v[162:163]
	s_nop 0
	v_addc_co_u32_e32 v5, vcc, 0, v3, vcc
	v_add_co_u32_e32 v2, vcc, 0x104c0000, v2
	s_and_b32 s43, s19, 1
	s_nop 0
	v_addc_co_u32_e32 v3, vcc, 0, v3, vcc
	v_add_co_u32_e32 v14, vcc, 0x12460000, v10
	global_load_dwordx4 v[6:9], v[4:5], off
	s_nop 0
	global_load_dwordx4 v[2:5], v[2:3], off
	v_addc_co_u32_e32 v15, vcc, 0, v11, vcc
	global_load_dwordx4 v[10:13], v[14:15], off offset:256
	global_load_dwordx4 v[108:111], v[14:15], off offset:384
	v_lshl_add_u64 v[14:15], s[22:23], 0, v[164:165]
	global_load_dwordx4 v[112:115], v[14:15], off
	s_mul_i32 s20, s43, 0x6800
	v_add_u32_e32 v1, s20, v175
	s_mul_i32 s20, s43, 0x4200
	v_add_u32_e32 v15, s20, v174
	v_add_u32_e32 v14, 0xd000, v15
	v_add_u32_e32 v176, 0xf000, v15
	ds_read_b128 v[116:119], v1 offset:0
	ds_read_b128 v[120:123], v1 offset:32
	ds_read_b128 v[124:127], v1 offset:64
	ds_read_b128 v[128:131], v1 offset:96
	ds_read_b128 v[132:135], v1 offset:128
	ds_read_b128 v[136:139], v1 offset:160
	s_waitcnt lgkmcnt(5)
	v_mfma_f32_32x32x16_bf16 v[64:79], v[116:119], v[84:87], v[198:213]
	s_waitcnt lgkmcnt(4)
	v_mfma_f32_32x32x16_bf16 v[64:79], v[120:123], v[88:91], v[64:79]
	s_waitcnt lgkmcnt(3)
	v_mfma_f32_32x32x16_bf16 v[64:79], v[124:127], v[92:95], v[64:79]
	s_waitcnt lgkmcnt(2)
	v_mfma_f32_32x32x16_bf16 v[64:79], v[128:131], v[96:99], v[64:79]
	s_waitcnt lgkmcnt(1)
	v_mfma_f32_32x32x16_bf16 v[64:79], v[132:135], v[100:103], v[64:79]
	s_waitcnt lgkmcnt(0)
	v_mfma_f32_32x32x16_bf16 v[64:79], v[136:139], v[104:107], v[64:79]
	s_waitcnt lgkmcnt(0)
	ds_read_b128 v[116:119], v1 offset:6656
	ds_read_b128 v[120:123], v1 offset:6688
	ds_read_b128 v[124:127], v1 offset:6720
	ds_read_b128 v[128:131], v1 offset:6752
	ds_read_b128 v[132:135], v1 offset:6784
	ds_read_b128 v[136:139], v1 offset:6816
	ds_read2_b64 v[140:143], v14 offset0:0 offset1:2
	ds_read2_b64 v[144:147], v176 offset0:32 offset1:34
	ds_read2_b64 v[180:183], v14 offset0:4 offset1:6
	ds_read2_b64 v[184:187], v176 offset0:36 offset1:38
	s_nop 1
	v_max3_f32 v15, v64, v65, v66
	v_max3_f32 v177, v67, v68, v69
	v_max3_f32 v15, v15, v70, v71
	v_max3_f32 v177, v177, v72, v73
	v_max3_f32 v15, v15, v74, v75
	v_max3_f32 v177, v177, v76, v77
	v_max3_f32 v15, v15, v78, v79
	v_max_f32_e32 v15, v15, v177
	v_mov_b32_e32 v177, v15
	v_mov_b32_e32 v178, v15
	s_nop 1
	v_permlane32_swap_b32_e32 v177, v178
	v_max3_f32 v15, v15, v177, v178
	v_cmp_gt_f32_e32 vcc, v15, v197
	s_cbranch_vccz .Lm3_ok1
	v_max_f32_e32 v15, v171, v15
	v_sub_f32_e32 v177, v171, v15
	v_exp_f32_e32 v177, v177
	v_sub_f32_e32 v198, v198, v15
	s_and_saveexec_b64 s[20:21], s[40:41]
	ds_write_b32 v149, v177
	s_or_b64 exec, exec, s[20:21]
	v_mul_f32_e32 v170, v170, v177
	v_add_u32_e32 v178, s25, v148
	s_waitcnt lgkmcnt(0)
	ds_read_b128 v[188:191], v178
	ds_read_b128 v[192:195], v178 offset:32
	ds_read_b128 v[222:225], v178 offset:64
	ds_read_b128 v[236:239], v178 offset:96
	v_sub_f32_e32 v64, v64, v15
	v_sub_f32_e32 v65, v65, v15
	v_sub_f32_e32 v66, v66, v15
	v_sub_f32_e32 v67, v67, v15
	v_sub_f32_e32 v68, v68, v15
	v_sub_f32_e32 v69, v69, v15
	v_sub_f32_e32 v70, v70, v15
	v_sub_f32_e32 v71, v71, v15
	v_sub_f32_e32 v72, v72, v15
	v_sub_f32_e32 v73, v73, v15
	v_sub_f32_e32 v74, v74, v15
	v_sub_f32_e32 v75, v75, v15
	v_sub_f32_e32 v76, v76, v15
	v_sub_f32_e32 v77, v77, v15
	v_sub_f32_e32 v78, v78, v15
	v_sub_f32_e32 v79, v79, v15
	v_mov_b32_e32 v199, v198
	v_mov_b32_e32 v200, v198
	v_mov_b32_e32 v201, v198
	v_mov_b32_e32 v202, v198
	v_mov_b32_e32 v203, v198
	v_mov_b32_e32 v204, v198
	v_mov_b32_e32 v205, v198
	v_mov_b32_e32 v206, v198
	v_mov_b32_e32 v207, v198
	v_mov_b32_e32 v208, v198
	v_mov_b32_e32 v209, v198
	v_mov_b32_e32 v210, v198
	v_mov_b32_e32 v211, v198
	v_mov_b32_e32 v212, v198
	v_mov_b32_e32 v213, v198
	v_mov_b32_e32 v171, 0
	v_mov_b32_e32 v197, 0x41000000
	s_nop 11
	s_nop 3
	s_waitcnt lgkmcnt(0)
	v_pk_mul_f32 v[16:17], v[16:17], v[188:189]
	v_pk_mul_f32 v[32:33], v[32:33], v[188:189]
	v_pk_mul_f32 v[18:19], v[18:19], v[190:191]
	v_pk_mul_f32 v[34:35], v[34:35], v[190:191]
	v_pk_mul_f32 v[20:21], v[20:21], v[192:193]
	v_pk_mul_f32 v[36:37], v[36:37], v[192:193]
	v_pk_mul_f32 v[22:23], v[22:23], v[194:195]
	v_pk_mul_f32 v[38:39], v[38:39], v[194:195]
	v_pk_mul_f32 v[24:25], v[24:25], v[222:223]
	v_pk_mul_f32 v[40:41], v[40:41], v[222:223]
	v_pk_mul_f32 v[26:27], v[26:27], v[224:225]
	v_pk_mul_f32 v[42:43], v[42:43], v[224:225]
	v_pk_mul_f32 v[28:29], v[28:29], v[236:237]
	v_pk_mul_f32 v[44:45], v[44:45], v[236:237]
	v_pk_mul_f32 v[30:31], v[30:31], v[238:239]
	v_pk_mul_f32 v[46:47], v[46:47], v[238:239]
; #define LAS __attribute__((address_space(3)))
; __device__ __forceinline__ unsigned pk2(float lo, float hi) { f32x2_t v = {lo, hi}; bf16x2_t b = __builtin_convertvector(v, bf16x2_t); return __builtin_bit_cast(unsigned, b); }
; __device__ __forceinline__ float ex2(float x) { return __builtin_amdgcn_exp2f(x); }
; template <bool MASK> __device__ __forceinline__ void sm_tile(f32x16& p0, f32x16& p1, float& mrun, float& lrun, f32x16& o0, f32x16& o1, LAS float* wsf, int kv0, int qpos, int q32, int hi) {
;     ...
;     float rs = 0.f;
; #pragma unroll
;     for (int r = 0; r < 16; ++r) { p0[r] = ex2(p0[r] - mrun); p1[r] = ex2(p1[r] - mrun); rs += p0[r] + p1[r]; }
;     rs += xhalf(rs, hi); lrun += rs;
; template <bool MASK> __device__ __forceinline__ void sm_iter(int var, SmState& st, const bf16x8 (&qr)[6], const LAS unsigned char* kb, const LAS unsigned char* vb, LAS float* wsf, int kv0, int qpos, int q32, int hi) {
;     ...
; #pragma unroll
;     for (int d0 = 0; d0 < ND; ++d0) { p0 = MFMA32(kf[2 * d0], qr[d0], p0); p1 = MFMA32(kf[2 * d0 + 1], qr[d0], p1); }
; #pragma unroll
;     for (int j = 0; j < 4; ++j) { vlo[2 * j] = *(const LAS s16x4*)(vb + j * 32); vhh[2 * j] = *(const LAS s16x4*)(vb + j * 32 + 16);
;         vlo[2 * j + 1] = *(const LAS s16x4*)(vb + 32 * VP + j * 32); vhh[2 * j + 1] = *(const LAS s16x4*)(vb + 32 * VP + j * 32 + 16); }
;     __builtin_amdgcn_sched_barrier(0);
;     if (var != 1) sm_tile<MASK>(p0, p1, st.mrun, st.lrun, st.o0, st.o1, wsf, kv0, qpos, q32, hi);
; #pragma unroll
;     for (int j = 0; j < 4; ++j) {
;         u32x4 pw;
;         if (j < 2) { const int r0 = 8 * (j & 1); pw.x = pk2(p0[r0], p0[r0 + 1]); pw.y = pk2(p0[r0 + 2], p0[r0 + 3]); pw.z = pk2(p0[r0 + 4], p0[r0 + 5]); pw.w = pk2(p0[r0 + 6], p0[r0 + 7]); }
;         else { const int r0 = 8 * (j & 1); pw.x = pk2(p1[r0], p1[r0 + 1]); pw.y = pk2(p1[r0 + 2], p1[r0 + 3]); pw.z = pk2(p1[r0 + 4], p1[r0 + 5]); pw.w = pk2(p1[r0 + 6], p1[r0 + 7]); }
;         const bf16x8 pa = __builtin_bit_cast(bf16x8, pw);
;         { const s16x4 lo = vlo[2 * j], hh = vhh[2 * j]; const bf16x8 vf = {lo[0], lo[1], lo[2], lo[3], hh[0], hh[1], hh[2], hh[3]}; st.o0 = MFMA32(pa, vf, st.o0); }
;         { const s16x4 lo = vlo[2 * j + 1], hh = vhh[2 * j + 1]; const bf16x8 vf = {lo[0], lo[1], lo[2], lo[3], hh[0], hh[1], hh[2], hh[3]}; st.o1 = MFMA32(pa, vf, st.o1); }
;     }
.Lm3_ok1:
.Lm3_body:
	v_exp_f32_e32 v64, v64
	v_exp_f32_e32 v65, v65
	v_exp_f32_e32 v66, v66
	s_waitcnt lgkmcnt(9)
	v_mfma_f32_32x32x16_bf16 v[48:63], v[116:119], v[84:87], v[198:213]
	v_add_f32_e32 v15, v64, v65
	v_exp_f32_e32 v67, v67
	v_cvt_pk_bf16_f32 v214, v64, v65
	v_exp_f32_e32 v68, v68
	v_add_f32_e32 v177, v66, v67
	v_exp_f32_e32 v69, v69
	v_cvt_pk_bf16_f32 v215, v66, v67
	s_waitcnt lgkmcnt(8)
	v_mfma_f32_32x32x16_bf16 v[48:63], v[120:123], v[88:91], v[48:63]
	v_exp_f32_e32 v70, v70
	v_add_f32_e32 v15, v15, v68
	v_exp_f32_e32 v71, v71
	v_add_f32_e32 v177, v177, v69
	v_exp_f32_e32 v72, v72
	v_cvt_pk_bf16_f32 v216, v68, v69
	s_waitcnt lgkmcnt(7)
	v_mfma_f32_32x32x16_bf16 v[48:63], v[124:127], v[92:95], v[48:63]
	v_exp_f32_e32 v73, v73
	v_add_f32_e32 v15, v15, v70
	v_exp_f32_e32 v74, v74
	v_add_f32_e32 v177, v177, v71
	v_exp_f32_e32 v75, v75
	v_cvt_pk_bf16_f32 v217, v70, v71
	s_waitcnt lgkmcnt(6)
	v_mfma_f32_32x32x16_bf16 v[48:63], v[128:131], v[96:99], v[48:63]
	v_exp_f32_e32 v76, v76
	v_add_f32_e32 v15, v15, v72
	v_exp_f32_e32 v77, v77
	v_add_f32_e32 v177, v177, v73
	v_exp_f32_e32 v78, v78
	v_cvt_pk_bf16_f32 v218, v72, v73
	s_waitcnt lgkmcnt(5)
	v_mfma_f32_32x32x16_bf16 v[48:63], v[132:135], v[100:103], v[48:63]
	v_exp_f32_e32 v79, v79
	v_add_f32_e32 v15, v15, v74
	v_add_f32_e32 v177, v177, v75
	v_cvt_pk_bf16_f32 v219, v74, v75
	v_add_f32_e32 v15, v15, v76
	v_add_f32_e32 v177, v177, v77
	s_waitcnt lgkmcnt(4)
	v_mfma_f32_32x32x16_bf16 v[48:63], v[136:139], v[104:107], v[48:63]
	v_cvt_pk_bf16_f32 v220, v76, v77
	v_add_f32_e32 v15, v15, v78
	v_add_f32_e32 v177, v177, v79
	v_cvt_pk_bf16_f32 v221, v78, v79
	v_add_f32_e32 v15, v15, v177
	v_add_f32_e32 v170, v170, v15
	s_waitcnt lgkmcnt(0)
	ds_read_b128 v[116:119], v1 offset:13312
	ds_read_b128 v[120:123], v1 offset:13344
	ds_read_b128 v[124:127], v1 offset:13376
	ds_read_b128 v[128:131], v1 offset:13408
	ds_read_b128 v[132:135], v1 offset:13440
	ds_read_b128 v[136:139], v1 offset:13472
	v_mfma_f32_32x32x16_bf16 v[16:31], v[214:217], v[140:143], v[16:31]
	ds_read2_b64 v[140:143], v14 offset0:8 offset1:10
	v_mfma_f32_32x32x16_bf16 v[32:47], v[214:217], v[144:147], v[32:47]
	ds_read2_b64 v[144:147], v176 offset0:40 offset1:42
	v_mfma_f32_32x32x16_bf16 v[16:31], v[218:221], v[180:183], v[16:31]
	ds_read2_b64 v[180:183], v14 offset0:12 offset1:14
	v_mfma_f32_32x32x16_bf16 v[32:47], v[218:221], v[184:187], v[32:47]
	ds_read2_b64 v[184:187], v176 offset0:44 offset1:46
	v_max3_f32 v15, v48, v49, v50
	v_max3_f32 v177, v51, v52, v53
	v_max3_f32 v15, v15, v54, v55
	v_max3_f32 v177, v177, v56, v57
	v_max3_f32 v15, v15, v58, v59
	v_max3_f32 v177, v177, v60, v61
	v_max3_f32 v15, v15, v62, v63
	v_max_f32_e32 v15, v15, v177
	v_mov_b32_e32 v177, v15
	v_mov_b32_e32 v178, v15
	s_nop 1
	v_permlane32_swap_b32_e32 v177, v178
	v_max3_f32 v15, v15, v177, v178
	v_cmp_gt_f32_e32 vcc, v15, v197
	s_cbranch_vccz .Lm3_ok2
	v_max_f32_e32 v15, v171, v15
	v_sub_f32_e32 v177, v171, v15
	v_exp_f32_e32 v177, v177
	v_sub_f32_e32 v198, v198, v15
	s_and_saveexec_b64 s[20:21], s[40:41]
	ds_write_b32 v149, v177
	s_or_b64 exec, exec, s[20:21]
	v_mul_f32_e32 v170, v170, v177
	v_add_u32_e32 v178, s25, v148
	s_waitcnt lgkmcnt(0)
	ds_read_b128 v[188:191], v178
	ds_read_b128 v[192:195], v178 offset:32
	ds_read_b128 v[222:225], v178 offset:64
	ds_read_b128 v[236:239], v178 offset:96
	v_sub_f32_e32 v48, v48, v15
	v_sub_f32_e32 v49, v49, v15
	v_sub_f32_e32 v50, v50, v15
	v_sub_f32_e32 v51, v51, v15
	v_sub_f32_e32 v52, v52, v15
	v_sub_f32_e32 v53, v53, v15
	v_sub_f32_e32 v54, v54, v15
	v_sub_f32_e32 v55, v55, v15
	v_sub_f32_e32 v56, v56, v15
	v_sub_f32_e32 v57, v57, v15
	v_sub_f32_e32 v58, v58, v15
	v_sub_f32_e32 v59, v59, v15
	v_sub_f32_e32 v60, v60, v15
	v_sub_f32_e32 v61, v61, v15
	v_sub_f32_e32 v62, v62, v15
	v_sub_f32_e32 v63, v63, v15
	v_mov_b32_e32 v199, v198
	v_mov_b32_e32 v200, v198
	v_mov_b32_e32 v201, v198
	v_mov_b32_e32 v202, v198
	v_mov_b32_e32 v203, v198
	v_mov_b32_e32 v204, v198
	v_mov_b32_e32 v205, v198
	v_mov_b32_e32 v206, v198
	v_mov_b32_e32 v207, v198
	v_mov_b32_e32 v208, v198
	v_mov_b32_e32 v209, v198
	v_mov_b32_e32 v210, v198
	v_mov_b32_e32 v211, v198
	v_mov_b32_e32 v212, v198
	v_mov_b32_e32 v213, v198
	v_mov_b32_e32 v171, 0
	v_mov_b32_e32 v197, 0x41000000
	s_nop 11
	s_nop 3
	s_waitcnt lgkmcnt(0)
	v_pk_mul_f32 v[16:17], v[16:17], v[188:189]
	v_pk_mul_f32 v[32:33], v[32:33], v[188:189]
	v_pk_mul_f32 v[18:19], v[18:19], v[190:191]
	v_pk_mul_f32 v[34:35], v[34:35], v[190:191]
	v_pk_mul_f32 v[20:21], v[20:21], v[192:193]
	v_pk_mul_f32 v[36:37], v[36:37], v[192:193]
	v_pk_mul_f32 v[22:23], v[22:23], v[194:195]
	v_pk_mul_f32 v[38:39], v[38:39], v[194:195]
	v_pk_mul_f32 v[24:25], v[24:25], v[222:223]
	v_pk_mul_f32 v[40:41], v[40:41], v[222:223]
	v_pk_mul_f32 v[26:27], v[26:27], v[224:225]
	v_pk_mul_f32 v[42:43], v[42:43], v[224:225]
	v_pk_mul_f32 v[28:29], v[28:29], v[236:237]
	v_pk_mul_f32 v[44:45], v[44:45], v[236:237]
	v_pk_mul_f32 v[30:31], v[30:31], v[238:239]
	v_pk_mul_f32 v[46:47], v[46:47], v[238:239]
; #define LAS __attribute__((address_space(3)))
; template <bool MASK> __device__ __forceinline__ void sm_tile(f32x16& p0, f32x16& p1, float& mrun, float& lrun, f32x16& o0, f32x16& o1, LAS float* wsf, int kv0, int qpos, int q32, int hi) {
;     ...
;     float rm = fmaxf(p0[0], p1[0]);
; #pragma unroll
;     for (int r = 1; r < 16; ++r) rm = fmaxf(rm, fmaxf(p0[r], p1[r]));
;     rm = fmaxf(rm, xhalf(rm, hi));
;     if (__any(rm > mrun + 8.0f)) {
;         const float mnew = fmaxf(mrun, rm), alpha = ex2(mrun - mnew); mrun = mnew; lrun *= alpha;
;         if (hi == 0) wsf[q32] = alpha;
;         __builtin_amdgcn_fence(__ATOMIC_RELEASE, "wavefront"); asm volatile("s_waitcnt lgkmcnt(0)" ::: "memory");
; #pragma unroll
; template <bool MASK> __device__ __forceinline__ void sm_iter(int var, SmState& st, const bf16x8 (&qr)[6], const LAS unsigned char* kb, const LAS unsigned char* vb, LAS float* wsf, int kv0, int qpos, int q32, int hi) {
;     ...
; #pragma unroll
;     for (int d0 = 0; d0 < ND; ++d0) { p0 = MFMA32(kf[2 * d0], qr[d0], p0); p1 = MFMA32(kf[2 * d0 + 1], qr[d0], p1); }
; #pragma unroll
;     for (int j = 0; j < 4; ++j) { vlo[2 * j] = *(const LAS s16x4*)(vb + j * 32); vhh[2 * j] = *(const LAS s16x4*)(vb + j * 32 + 16);
;         vlo[2 * j + 1] = *(const LAS s16x4*)(vb + 32 * VP + j * 32); vhh[2 * j + 1] = *(const LAS s16x4*)(vb + 32 * VP + j * 32 + 16); }
;     __builtin_amdgcn_sched_barrier(0);
;     if (var != 1) sm_tile<MASK>(p0, p1, st.mrun, st.lrun, st.o0, st.o1, wsf, kv0, qpos, q32, hi);
; #pragma unroll
;     for (int j = 0; j < 4; ++j) {
;         u32x4 pw;
;         if (j < 2) { const int r0 = 8 * (j & 1); pw.x = pk2(p0[r0], p0[r0 + 1]); pw.y = pk2(p0[r0 + 2], p0[r0 + 3]); pw.z = pk2(p0[r0 + 4], p0[r0 + 5]); pw.w = pk2(p0[r0 + 6], p0[r0 + 7]); }
;         else { const int r0 = 8 * (j & 1); pw.x = pk2(p1[r0], p1[r0 + 1]); pw.y = pk2(p1[r0 + 2], p1[r0 + 3]); pw.z = pk2(p1[r0 + 4], p1[r0 + 5]); pw.w = pk2(p1[r0 + 6], p1[r0 + 7]); }
;         const bf16x8 pa = __builtin_bit_cast(bf16x8, pw);
;         { const s16x4 lo = vlo[2 * j], hh = vhh[2 * j]; const bf16x8 vf = {lo[0], lo[1], lo[2], lo[3], hh[0], hh[1], hh[2], hh[3]}; st.o0 = MFMA32(pa, vf, st.o0); }
;         { const s16x4 lo = vlo[2 * j + 1], hh = vhh[2 * j + 1]; const bf16x8 vf = {lo[0], lo[1], lo[2], lo[3], hh[0], hh[1], hh[2], hh[3]}; st.o1 = MFMA32(pa, vf, st.o1); }
;     }
.Lm3_ok2:
	v_exp_f32_e32 v48, v48
	v_exp_f32_e32 v49, v49
	v_exp_f32_e32 v50, v50
	s_waitcnt lgkmcnt(9)
	v_mfma_f32_32x32x16_bf16 v[64:79], v[116:119], v[84:87], v[198:213]
	v_add_f32_e32 v15, v48, v49
	v_exp_f32_e32 v51, v51
	v_cvt_pk_bf16_f32 v214, v48, v49
	v_exp_f32_e32 v52, v52
	v_add_f32_e32 v177, v50, v51
	v_exp_f32_e32 v53, v53
	v_cvt_pk_bf16_f32 v215, v50, v51
	s_waitcnt lgkmcnt(8)
	v_mfma_f32_32x32x16_bf16 v[64:79], v[120:123], v[88:91], v[64:79]
	v_exp_f32_e32 v54, v54
	v_add_f32_e32 v15, v15, v52
	v_exp_f32_e32 v55, v55
	v_add_f32_e32 v177, v177, v53
	v_exp_f32_e32 v56, v56
	v_cvt_pk_bf16_f32 v216, v52, v53
	s_waitcnt lgkmcnt(7)
	v_mfma_f32_32x32x16_bf16 v[64:79], v[124:127], v[92:95], v[64:79]
	v_exp_f32_e32 v57, v57
	v_add_f32_e32 v15, v15, v54
	v_exp_f32_e32 v58, v58
	v_add_f32_e32 v177, v177, v55
	v_exp_f32_e32 v59, v59
	v_cvt_pk_bf16_f32 v217, v54, v55
	s_waitcnt lgkmcnt(6)
	v_mfma_f32_32x32x16_bf16 v[64:79], v[128:131], v[96:99], v[64:79]
	v_exp_f32_e32 v60, v60
	v_add_f32_e32 v15, v15, v56
	v_exp_f32_e32 v61, v61
	v_add_f32_e32 v177, v177, v57
	v_exp_f32_e32 v62, v62
	v_cvt_pk_bf16_f32 v218, v56, v57
	s_waitcnt lgkmcnt(5)
	v_mfma_f32_32x32x16_bf16 v[64:79], v[132:135], v[100:103], v[64:79]
	v_exp_f32_e32 v63, v63
	v_add_f32_e32 v15, v15, v58
	v_add_f32_e32 v177, v177, v59
	v_cvt_pk_bf16_f32 v219, v58, v59
	v_add_f32_e32 v15, v15, v60
	v_add_f32_e32 v177, v177, v61
	s_waitcnt lgkmcnt(4)
	v_mfma_f32_32x32x16_bf16 v[64:79], v[136:139], v[104:107], v[64:79]
	v_cvt_pk_bf16_f32 v220, v60, v61
	v_add_f32_e32 v15, v15, v62
	v_add_f32_e32 v177, v177, v63
	v_cvt_pk_bf16_f32 v221, v62, v63
	v_add_f32_e32 v15, v15, v177
	v_add_f32_e32 v170, v170, v15
	s_waitcnt lgkmcnt(0)
	ds_read_b128 v[116:119], v1 offset:19968
	ds_read_b128 v[120:123], v1 offset:20000
	ds_read_b128 v[124:127], v1 offset:20032
	ds_read_b128 v[128:131], v1 offset:20064
	ds_read_b128 v[132:135], v1 offset:20096
	ds_read_b128 v[136:139], v1 offset:20128
	v_mfma_f32_32x32x16_bf16 v[16:31], v[214:217], v[140:143], v[16:31]
	ds_read2_b64 v[140:143], v14 offset0:16 offset1:18
	v_mfma_f32_32x32x16_bf16 v[32:47], v[214:217], v[144:147], v[32:47]
	ds_read2_b64 v[144:147], v176 offset0:48 offset1:50
	v_mfma_f32_32x32x16_bf16 v[16:31], v[218:221], v[180:183], v[16:31]
	ds_read2_b64 v[180:183], v14 offset0:20 offset1:22
	v_mfma_f32_32x32x16_bf16 v[32:47], v[218:221], v[184:187], v[32:47]
	ds_read2_b64 v[184:187], v176 offset0:52 offset1:54
	v_max3_f32 v15, v64, v65, v66
	v_max3_f32 v177, v67, v68, v69
	v_max3_f32 v15, v15, v70, v71
	v_max3_f32 v177, v177, v72, v73
	v_max3_f32 v15, v15, v74, v75
	v_max3_f32 v177, v177, v76, v77
	v_max3_f32 v15, v15, v78, v79
	v_max_f32_e32 v15, v15, v177
	v_mov_b32_e32 v177, v15
	v_mov_b32_e32 v178, v15
	s_nop 1
	v_permlane32_swap_b32_e32 v177, v178
	v_max3_f32 v15, v15, v177, v178
	v_cmp_gt_f32_e32 vcc, v15, v197
	s_cbranch_vccz .Lm3_ok3
	v_max_f32_e32 v15, v171, v15
	v_sub_f32_e32 v177, v171, v15
	v_exp_f32_e32 v177, v177
	v_sub_f32_e32 v198, v198, v15
	s_and_saveexec_b64 s[20:21], s[40:41]
	ds_write_b32 v149, v177
	s_or_b64 exec, exec, s[20:21]
	v_mul_f32_e32 v170, v170, v177
	v_add_u32_e32 v178, s25, v148
	s_waitcnt lgkmcnt(0)
	ds_read_b128 v[188:191], v178
	ds_read_b128 v[192:195], v178 offset:32
	ds_read_b128 v[222:225], v178 offset:64
	ds_read_b128 v[236:239], v178 offset:96
	v_sub_f32_e32 v64, v64, v15
	v_sub_f32_e32 v65, v65, v15
	v_sub_f32_e32 v66, v66, v15
	v_sub_f32_e32 v67, v67, v15
	v_sub_f32_e32 v68, v68, v15
	v_sub_f32_e32 v69, v69, v15
	v_sub_f32_e32 v70, v70, v15
	v_sub_f32_e32 v71, v71, v15
	v_sub_f32_e32 v72, v72, v15
	v_sub_f32_e32 v73, v73, v15
	v_sub_f32_e32 v74, v74, v15
	v_sub_f32_e32 v75, v75, v15
	v_sub_f32_e32 v76, v76, v15
	v_sub_f32_e32 v77, v77, v15
	v_sub_f32_e32 v78, v78, v15
	v_sub_f32_e32 v79, v79, v15
	v_mov_b32_e32 v199, v198
	v_mov_b32_e32 v200, v198
	v_mov_b32_e32 v201, v198
	v_mov_b32_e32 v202, v198
	v_mov_b32_e32 v203, v198
	v_mov_b32_e32 v204, v198
	v_mov_b32_e32 v205, v198
	v_mov_b32_e32 v206, v198
	v_mov_b32_e32 v207, v198
	v_mov_b32_e32 v208, v198
	v_mov_b32_e32 v209, v198
	v_mov_b32_e32 v210, v198
	v_mov_b32_e32 v211, v198
	v_mov_b32_e32 v212, v198
	v_mov_b32_e32 v213, v198
	v_mov_b32_e32 v171, 0
	v_mov_b32_e32 v197, 0x41000000
	s_nop 11
	s_nop 3
	s_waitcnt lgkmcnt(0)
	v_pk_mul_f32 v[16:17], v[16:17], v[188:189]
	v_pk_mul_f32 v[32:33], v[32:33], v[188:189]
	v_pk_mul_f32 v[18:19], v[18:19], v[190:191]
	v_pk_mul_f32 v[34:35], v[34:35], v[190:191]
	v_pk_mul_f32 v[20:21], v[20:21], v[192:193]
	v_pk_mul_f32 v[36:37], v[36:37], v[192:193]
	v_pk_mul_f32 v[22:23], v[22:23], v[194:195]
	v_pk_mul_f32 v[38:39], v[38:39], v[194:195]
	v_pk_mul_f32 v[24:25], v[24:25], v[222:223]
	v_pk_mul_f32 v[40:41], v[40:41], v[222:223]
	v_pk_mul_f32 v[26:27], v[26:27], v[224:225]
	v_pk_mul_f32 v[42:43], v[42:43], v[224:225]
	v_pk_mul_f32 v[28:29], v[28:29], v[236:237]
	v_pk_mul_f32 v[44:45], v[44:45], v[236:237]
	v_pk_mul_f32 v[30:31], v[30:31], v[238:239]
	v_pk_mul_f32 v[46:47], v[46:47], v[238:239]
; #define LAS __attribute__((address_space(3)))
; template <bool MASK> __device__ __forceinline__ void sm_tile(f32x16& p0, f32x16& p1, float& mrun, float& lrun, f32x16& o0, f32x16& o1, LAS float* wsf, int kv0, int qpos, int q32, int hi) {
;     ...
;     float rm = fmaxf(p0[0], p1[0]);
; #pragma unroll
;     for (int r = 1; r < 16; ++r) rm = fmaxf(rm, fmaxf(p0[r], p1[r]));
;     rm = fmaxf(rm, xhalf(rm, hi));
;     if (__any(rm > mrun + 8.0f)) {
;         const float mnew = fmaxf(mrun, rm), alpha = ex2(mrun - mnew); mrun = mnew; lrun *= alpha;
;         if (hi == 0) wsf[q32] = alpha;
;         __builtin_amdgcn_fence(__ATOMIC_RELEASE, "wavefront"); asm volatile("s_waitcnt lgkmcnt(0)" ::: "memory");
; #pragma unroll
; template <bool MASK> __device__ __forceinline__ void sm_iter(int var, SmState& st, const bf16x8 (&qr)[6], const LAS unsigned char* kb, const LAS unsigned char* vb, LAS float* wsf, int kv0, int qpos, int q32, int hi) {
;     ...
; #pragma unroll
;     for (int d0 = 0; d0 < ND; ++d0) { p0 = MFMA32(kf[2 * d0], qr[d0], p0); p1 = MFMA32(kf[2 * d0 + 1], qr[d0], p1); }
; #pragma unroll
;     for (int j = 0; j < 4; ++j) { vlo[2 * j] = *(const LAS s16x4*)(vb + j * 32); vhh[2 * j] = *(const LAS s16x4*)(vb + j * 32 + 16);
;         vlo[2 * j + 1] = *(const LAS s16x4*)(vb + 32 * VP + j * 32); vhh[2 * j + 1] = *(const LAS s16x4*)(vb + 32 * VP + j * 32 + 16); }
;     __builtin_amdgcn_sched_barrier(0);
;     if (var != 1) sm_tile<MASK>(p0, p1, st.mrun, st.lrun, st.o0, st.o1, wsf, kv0, qpos, q32, hi);
; #pragma unroll
;     for (int j = 0; j < 4; ++j) {
;         u32x4 pw;
;         if (j < 2) { const int r0 = 8 * (j & 1); pw.x = pk2(p0[r0], p0[r0 + 1]); pw.y = pk2(p0[r0 + 2], p0[r0 + 3]); pw.z = pk2(p0[r0 + 4], p0[r0 + 5]); pw.w = pk2(p0[r0 + 6], p0[r0 + 7]); }
;         else { const int r0 = 8 * (j & 1); pw.x = pk2(p1[r0], p1[r0 + 1]); pw.y = pk2(p1[r0 + 2], p1[r0 + 3]); pw.z = pk2(p1[r0 + 4], p1[r0 + 5]); pw.w = pk2(p1[r0 + 6], p1[r0 + 7]); }
;         const bf16x8 pa = __builtin_bit_cast(bf16x8, pw);
;         { const s16x4 lo = vlo[2 * j], hh = vhh[2 * j]; const bf16x8 vf = {lo[0], lo[1], lo[2], lo[3], hh[0], hh[1], hh[2], hh[3]}; st.o0 = MFMA32(pa, vf, st.o0); }
;         { const s16x4 lo = vlo[2 * j + 1], hh = vhh[2 * j + 1]; const bf16x8 vf = {lo[0], lo[1], lo[2], lo[3], hh[0], hh[1], hh[2], hh[3]}; st.o1 = MFMA32(pa, vf, st.o1); }
;     }
.Lm3_ok3:
	v_exp_f32_e32 v64, v64
	v_exp_f32_e32 v65, v65
	v_exp_f32_e32 v66, v66
	s_waitcnt lgkmcnt(9)
	v_mfma_f32_32x32x16_bf16 v[48:63], v[116:119], v[84:87], v[198:213]
	v_add_f32_e32 v15, v64, v65
	v_exp_f32_e32 v67, v67
	v_cvt_pk_bf16_f32 v214, v64, v65
	v_exp_f32_e32 v68, v68
	v_add_f32_e32 v177, v66, v67
	v_exp_f32_e32 v69, v69
	v_cvt_pk_bf16_f32 v215, v66, v67
	s_waitcnt lgkmcnt(8)
	v_mfma_f32_32x32x16_bf16 v[48:63], v[120:123], v[88:91], v[48:63]
	v_exp_f32_e32 v70, v70
	v_add_f32_e32 v15, v15, v68
	v_exp_f32_e32 v71, v71
	v_add_f32_e32 v177, v177, v69
	v_exp_f32_e32 v72, v72
	v_cvt_pk_bf16_f32 v216, v68, v69
	s_waitcnt lgkmcnt(7)
	v_mfma_f32_32x32x16_bf16 v[48:63], v[124:127], v[92:95], v[48:63]
	v_exp_f32_e32 v73, v73
	v_add_f32_e32 v15, v15, v70
	v_exp_f32_e32 v74, v74
	v_add_f32_e32 v177, v177, v71
	v_exp_f32_e32 v75, v75
	v_cvt_pk_bf16_f32 v217, v70, v71
	s_waitcnt lgkmcnt(6)
	v_mfma_f32_32x32x16_bf16 v[48:63], v[128:131], v[96:99], v[48:63]
	v_exp_f32_e32 v76, v76
	v_add_f32_e32 v15, v15, v72
	v_exp_f32_e32 v77, v77
	v_add_f32_e32 v177, v177, v73
	v_exp_f32_e32 v78, v78
	v_cvt_pk_bf16_f32 v218, v72, v73
	s_waitcnt lgkmcnt(5)
	v_mfma_f32_32x32x16_bf16 v[48:63], v[132:135], v[100:103], v[48:63]
	v_exp_f32_e32 v79, v79
	v_add_f32_e32 v15, v15, v74
	v_add_f32_e32 v177, v177, v75
	v_cvt_pk_bf16_f32 v219, v74, v75
	v_add_f32_e32 v15, v15, v76
	v_add_f32_e32 v177, v177, v77
	s_waitcnt lgkmcnt(4)
	v_mfma_f32_32x32x16_bf16 v[48:63], v[136:139], v[104:107], v[48:63]
	v_cvt_pk_bf16_f32 v220, v76, v77
	v_add_f32_e32 v15, v15, v78
	v_add_f32_e32 v177, v177, v79
	v_cvt_pk_bf16_f32 v221, v78, v79
	v_add_f32_e32 v15, v15, v177
	v_add_f32_e32 v170, v170, v15
	s_waitcnt lgkmcnt(0)
	v_mfma_f32_32x32x16_bf16 v[16:31], v[214:217], v[140:143], v[16:31]
	ds_read2_b64 v[140:143], v14 offset0:24 offset1:26
	v_mfma_f32_32x32x16_bf16 v[32:47], v[214:217], v[144:147], v[32:47]
	ds_read2_b64 v[144:147], v176 offset0:56 offset1:58
	v_mfma_f32_32x32x16_bf16 v[16:31], v[218:221], v[180:183], v[16:31]
	ds_read2_b64 v[180:183], v14 offset0:28 offset1:30
	v_mfma_f32_32x32x16_bf16 v[32:47], v[218:221], v[184:187], v[32:47]
	ds_read2_b64 v[184:187], v176 offset0:60 offset1:62
	s_nop 3
	v_max3_f32 v15, v48, v49, v50
	v_max3_f32 v177, v51, v52, v53
	v_max3_f32 v15, v15, v54, v55
	v_max3_f32 v177, v177, v56, v57
	v_max3_f32 v15, v15, v58, v59
	v_max3_f32 v177, v177, v60, v61
	v_max3_f32 v15, v15, v62, v63
	v_max_f32_e32 v15, v15, v177
	v_mov_b32_e32 v177, v15
	v_mov_b32_e32 v178, v15
	s_nop 1
	v_permlane32_swap_b32_e32 v177, v178
	v_max3_f32 v15, v15, v177, v178
	v_cmp_gt_f32_e32 vcc, v15, v197
	s_cbranch_vccz .Lm3_ok4
	v_max_f32_e32 v15, v171, v15
	v_sub_f32_e32 v177, v171, v15
	v_exp_f32_e32 v177, v177
	v_sub_f32_e32 v198, v198, v15
	s_and_saveexec_b64 s[20:21], s[40:41]
	ds_write_b32 v149, v177
	s_or_b64 exec, exec, s[20:21]
	v_mul_f32_e32 v170, v170, v177
	v_add_u32_e32 v178, s25, v148
	s_waitcnt lgkmcnt(0)
	ds_read_b128 v[188:191], v178
	ds_read_b128 v[192:195], v178 offset:32
	ds_read_b128 v[222:225], v178 offset:64
	ds_read_b128 v[236:239], v178 offset:96
	v_sub_f32_e32 v48, v48, v15
	v_sub_f32_e32 v49, v49, v15
	v_sub_f32_e32 v50, v50, v15
	v_sub_f32_e32 v51, v51, v15
	v_sub_f32_e32 v52, v52, v15
	v_sub_f32_e32 v53, v53, v15
	v_sub_f32_e32 v54, v54, v15
	v_sub_f32_e32 v55, v55, v15
	v_sub_f32_e32 v56, v56, v15
	v_sub_f32_e32 v57, v57, v15
	v_sub_f32_e32 v58, v58, v15
	v_sub_f32_e32 v59, v59, v15
	v_sub_f32_e32 v60, v60, v15
	v_sub_f32_e32 v61, v61, v15
	v_sub_f32_e32 v62, v62, v15
	v_sub_f32_e32 v63, v63, v15
	v_mov_b32_e32 v199, v198
	v_mov_b32_e32 v200, v198
	v_mov_b32_e32 v201, v198
	v_mov_b32_e32 v202, v198
	v_mov_b32_e32 v203, v198
	v_mov_b32_e32 v204, v198
	v_mov_b32_e32 v205, v198
	v_mov_b32_e32 v206, v198
	v_mov_b32_e32 v207, v198
	v_mov_b32_e32 v208, v198
	v_mov_b32_e32 v209, v198
	v_mov_b32_e32 v210, v198
	v_mov_b32_e32 v211, v198
	v_mov_b32_e32 v212, v198
	v_mov_b32_e32 v213, v198
	v_mov_b32_e32 v171, 0
	v_mov_b32_e32 v197, 0x41000000
	s_nop 11
	s_nop 3
	s_waitcnt lgkmcnt(0)
	v_pk_mul_f32 v[16:17], v[16:17], v[188:189]
	v_pk_mul_f32 v[32:33], v[32:33], v[188:189]
	v_pk_mul_f32 v[18:19], v[18:19], v[190:191]
	v_pk_mul_f32 v[34:35], v[34:35], v[190:191]
	v_pk_mul_f32 v[20:21], v[20:21], v[192:193]
	v_pk_mul_f32 v[36:37], v[36:37], v[192:193]
	v_pk_mul_f32 v[22:23], v[22:23], v[194:195]
	v_pk_mul_f32 v[38:39], v[38:39], v[194:195]
	v_pk_mul_f32 v[24:25], v[24:25], v[222:223]
	v_pk_mul_f32 v[40:41], v[40:41], v[222:223]
	v_pk_mul_f32 v[26:27], v[26:27], v[224:225]
	v_pk_mul_f32 v[42:43], v[42:43], v[224:225]
	v_pk_mul_f32 v[28:29], v[28:29], v[236:237]
	v_pk_mul_f32 v[44:45], v[44:45], v[236:237]
	v_pk_mul_f32 v[30:31], v[30:31], v[238:239]
	v_pk_mul_f32 v[46:47], v[46:47], v[238:239]
; #define SM_LOAD(js) do { kreg0 = *(const u32x4*)(kg + (long)(js) * 128 * ldk); kreg1 = *(const u32x4*)(kg + ((long)(js) * 128 + 64) * ldk); vreg0 = *(const u32x4*)(vg + (js) * 128); vreg1 = *(const u32x4*)(vg + (js) * 128 + 64); \
;         k2reg = *(const u32x4*)(k2g + (long)(js) * 128 * 32); } while (0)
; __device__ __forceinline__ void attn_unit_sm(int b, int h, int qb, const bf16_t* __restrict__ Q, const bf16_t* __restrict__ K, const bf16_t* __restrict__ K2, const bf16_t* __restrict__ Vt, bf16_t* __restrict__ O, const float* __restrict__ cs, LAS unsigned char* lds, int var) {
;     ...
;     for (; it < ns - 2; ++it) {
;         const int cur = it & 1;
;         if (var != 2) SM_LOAD(it + 1);
; #pragma unroll
;         for (int sub = 0; sub < 2; ++sub)
;             sm_iter<false>(var, st, qr, lds + OFF_K + cur * KBUF + (sub * 64 + q32) * KP + hi * 16, lds + OFF_V + cur * VBUF + q32 * VP + sub * 128 + hi * 8, wsf, (2 * it + sub) * 64, qpos, q32, hi);
;         if (var != 2) SM_STORE(cur ^ 1);
;         __syncthreads();
.Lm3_ok4:
	s_xor_b32 s20, s43, 1
	s_mul_i32 s21, s20, 0x6800
	s_add_i32 s21, s21, 0
	s_mulk_i32 s20, 0x4200
	s_add_i32 s19, s19, 1
	v_lshl_add_u64 v[162:163], v[162:163], 0, s[94:95]
	v_lshl_add_u64 v[164:165], v[164:165], 0, s[96:97]
	v_lshl_add_u64 v[166:167], v[166:167], 0, s[38:39]
	s_cmp_eq_u32 s18, s19
	v_add_u32_e32 v1, s21, v150
	s_waitcnt vmcnt(4)
	ds_write_b128 v1, v[6:9]
	s_waitcnt vmcnt(3)
	ds_write_b128 v1, v[2:5] offset:13312
	v_add_u32_e32 v1, s21, v152
	s_waitcnt vmcnt(0)
	ds_write_b128 v1, v[112:115] offset:128
	v_add_u32_e32 v1, s20, v151
	v_add_u32_e32 v14, 0xd000, v1
	v_add_u32_e32 v1, 0xd080, v1
	ds_write2_b64 v14, v[10:11], v[12:13] offset1:1
	ds_write2_b64 v1, v[108:109], v[110:111] offset1:1
	s_waitcnt lgkmcnt(0)
	s_barrier
	s_cbranch_scc1 .Lm3_drain
	v_lshl_add_u64 v[2:3], s[22:23], 0, v[166:167]
	v_add_co_u32_e32 v4, vcc, 0x104a0000, v2
	v_lshl_add_u64 v[10:11], s[22:23], 0, v[162:163]
	s_nop 0
	v_addc_co_u32_e32 v5, vcc, 0, v3, vcc
	v_add_co_u32_e32 v2, vcc, 0x104c0000, v2
	s_and_b32 s43, s19, 1
	s_nop 0
	v_addc_co_u32_e32 v3, vcc, 0, v3, vcc
	v_add_co_u32_e32 v14, vcc, 0x12460000, v10
	global_load_dwordx4 v[6:9], v[4:5], off
	s_nop 0
	global_load_dwordx4 v[2:5], v[2:3], off
	v_addc_co_u32_e32 v15, vcc, 0, v11, vcc
	global_load_dwordx4 v[10:13], v[14:15], off offset:256
	global_load_dwordx4 v[108:111], v[14:15], off offset:384
	v_lshl_add_u64 v[14:15], s[22:23], 0, v[164:165]
	global_load_dwordx4 v[112:115], v[14:15], off
	s_mul_i32 s20, s43, 0x6800
	v_add_u32_e32 v1, s20, v175
	s_mul_i32 s20, s43, 0x4200
	v_add_u32_e32 v15, s20, v174
	v_add_u32_e32 v14, 0xd000, v15
	v_add_u32_e32 v176, 0xf000, v15
	ds_read_b128 v[116:119], v1 offset:0
	ds_read_b128 v[120:123], v1 offset:32
	ds_read_b128 v[124:127], v1 offset:64
	ds_read_b128 v[128:131], v1 offset:96
	ds_read_b128 v[132:135], v1 offset:128
	ds_read_b128 v[136:139], v1 offset:160
	v_exp_f32_e32 v48, v48
	v_exp_f32_e32 v49, v49
	v_exp_f32_e32 v50, v50
	s_waitcnt lgkmcnt(5)
	v_mfma_f32_32x32x16_bf16 v[64:79], v[116:119], v[84:87], v[198:213]
	v_add_f32_e32 v15, v48, v49
	v_exp_f32_e32 v51, v51
	v_cvt_pk_bf16_f32 v214, v48, v49
	v_exp_f32_e32 v52, v52
	v_add_f32_e32 v177, v50, v51
	v_exp_f32_e32 v53, v53
	v_cvt_pk_bf16_f32 v215, v50, v51
	s_waitcnt lgkmcnt(4)
	v_mfma_f32_32x32x16_bf16 v[64:79], v[120:123], v[88:91], v[64:79]
	v_exp_f32_e32 v54, v54
	v_add_f32_e32 v15, v15, v52
	v_exp_f32_e32 v55, v55
	v_add_f32_e32 v177, v177, v53
	v_exp_f32_e32 v56, v56
	v_cvt_pk_bf16_f32 v216, v52, v53
	s_waitcnt lgkmcnt(3)
	v_mfma_f32_32x32x16_bf16 v[64:79], v[124:127], v[92:95], v[64:79]
	v_exp_f32_e32 v57, v57
	v_add_f32_e32 v15, v15, v54
	v_exp_f32_e32 v58, v58
	v_add_f32_e32 v177, v177, v55
	v_exp_f32_e32 v59, v59
	v_cvt_pk_bf16_f32 v217, v54, v55
	s_waitcnt lgkmcnt(2)
	v_mfma_f32_32x32x16_bf16 v[64:79], v[128:131], v[96:99], v[64:79]
	v_exp_f32_e32 v60, v60
	v_add_f32_e32 v15, v15, v56
	v_exp_f32_e32 v61, v61
	v_add_f32_e32 v177, v177, v57
	v_exp_f32_e32 v62, v62
	v_cvt_pk_bf16_f32 v218, v56, v57
	s_waitcnt lgkmcnt(1)
	v_mfma_f32_32x32x16_bf16 v[64:79], v[132:135], v[100:103], v[64:79]
	v_exp_f32_e32 v63, v63
	v_add_f32_e32 v15, v15, v58
	v_add_f32_e32 v177, v177, v59
	v_cvt_pk_bf16_f32 v219, v58, v59
	v_add_f32_e32 v15, v15, v60
	v_add_f32_e32 v177, v177, v61
	s_waitcnt lgkmcnt(0)
	v_mfma_f32_32x32x16_bf16 v[64:79], v[136:139], v[104:107], v[64:79]
	v_cvt_pk_bf16_f32 v220, v60, v61
	v_add_f32_e32 v15, v15, v62
	v_add_f32_e32 v177, v177, v63
	v_cvt_pk_bf16_f32 v221, v62, v63
	v_add_f32_e32 v15, v15, v177
	v_add_f32_e32 v170, v170, v15
	s_waitcnt lgkmcnt(0)
	ds_read_b128 v[116:119], v1 offset:6656
	ds_read_b128 v[120:123], v1 offset:6688
	ds_read_b128 v[124:127], v1 offset:6720
	ds_read_b128 v[128:131], v1 offset:6752
	ds_read_b128 v[132:135], v1 offset:6784
	ds_read_b128 v[136:139], v1 offset:6816
	v_mfma_f32_32x32x16_bf16 v[16:31], v[214:217], v[140:143], v[16:31]
	ds_read2_b64 v[140:143], v14 offset0:0 offset1:2
	v_mfma_f32_32x32x16_bf16 v[32:47], v[214:217], v[144:147], v[32:47]
	ds_read2_b64 v[144:147], v176 offset0:32 offset1:34
	v_mfma_f32_32x32x16_bf16 v[16:31], v[218:221], v[180:183], v[16:31]
	ds_read2_b64 v[180:183], v14 offset0:4 offset1:6
	v_mfma_f32_32x32x16_bf16 v[32:47], v[218:221], v[184:187], v[32:47]
	ds_read2_b64 v[184:187], v176 offset0:36 offset1:38
	v_max3_f32 v15, v64, v65, v66
	v_max3_f32 v177, v67, v68, v69
	v_max3_f32 v15, v15, v70, v71
	v_max3_f32 v177, v177, v72, v73
	v_max3_f32 v15, v15, v74, v75
	v_max3_f32 v177, v177, v76, v77
	v_max3_f32 v15, v15, v78, v79
	v_max_f32_e32 v15, v15, v177
	v_mov_b32_e32 v177, v15
	v_mov_b32_e32 v178, v15
	s_nop 1
	v_permlane32_swap_b32_e32 v177, v178
	v_max3_f32 v15, v15, v177, v178
	v_cmp_gt_f32_e32 vcc, v15, v197
	s_cbranch_vccz .Lm3_ok5
	v_max_f32_e32 v15, v171, v15
	v_sub_f32_e32 v177, v171, v15
	v_exp_f32_e32 v177, v177
	v_sub_f32_e32 v198, v198, v15
	s_and_saveexec_b64 s[20:21], s[40:41]
	ds_write_b32 v149, v177
	s_or_b64 exec, exec, s[20:21]
	v_mul_f32_e32 v170, v170, v177
	v_add_u32_e32 v178, s25, v148
	s_waitcnt lgkmcnt(0)
	ds_read_b128 v[188:191], v178
	ds_read_b128 v[192:195], v178 offset:32
	ds_read_b128 v[222:225], v178 offset:64
	ds_read_b128 v[236:239], v178 offset:96
	v_sub_f32_e32 v64, v64, v15
	v_sub_f32_e32 v65, v65, v15
	v_sub_f32_e32 v66, v66, v15
	v_sub_f32_e32 v67, v67, v15
	v_sub_f32_e32 v68, v68, v15
	v_sub_f32_e32 v69, v69, v15
	v_sub_f32_e32 v70, v70, v15
	v_sub_f32_e32 v71, v71, v15
	v_sub_f32_e32 v72, v72, v15
	v_sub_f32_e32 v73, v73, v15
	v_sub_f32_e32 v74, v74, v15
	v_sub_f32_e32 v75, v75, v15
	v_sub_f32_e32 v76, v76, v15
	v_sub_f32_e32 v77, v77, v15
	v_sub_f32_e32 v78, v78, v15
	v_sub_f32_e32 v79, v79, v15
	v_mov_b32_e32 v199, v198
	v_mov_b32_e32 v200, v198
	v_mov_b32_e32 v201, v198
	v_mov_b32_e32 v202, v198
	v_mov_b32_e32 v203, v198
	v_mov_b32_e32 v204, v198
	v_mov_b32_e32 v205, v198
	v_mov_b32_e32 v206, v198
	v_mov_b32_e32 v207, v198
	v_mov_b32_e32 v208, v198
	v_mov_b32_e32 v209, v198
	v_mov_b32_e32 v210, v198
	v_mov_b32_e32 v211, v198
	v_mov_b32_e32 v212, v198
	v_mov_b32_e32 v213, v198
	v_mov_b32_e32 v171, 0
	v_mov_b32_e32 v197, 0x41000000
	s_nop 11
	s_nop 3
	s_waitcnt lgkmcnt(0)
	v_pk_mul_f32 v[16:17], v[16:17], v[188:189]
	v_pk_mul_f32 v[32:33], v[32:33], v[188:189]
	v_pk_mul_f32 v[18:19], v[18:19], v[190:191]
	v_pk_mul_f32 v[34:35], v[34:35], v[190:191]
	v_pk_mul_f32 v[20:21], v[20:21], v[192:193]
	v_pk_mul_f32 v[36:37], v[36:37], v[192:193]
	v_pk_mul_f32 v[22:23], v[22:23], v[194:195]
	v_pk_mul_f32 v[38:39], v[38:39], v[194:195]
	v_pk_mul_f32 v[24:25], v[24:25], v[222:223]
	v_pk_mul_f32 v[40:41], v[40:41], v[222:223]
	v_pk_mul_f32 v[26:27], v[26:27], v[224:225]
	v_pk_mul_f32 v[42:43], v[42:43], v[224:225]
	v_pk_mul_f32 v[28:29], v[28:29], v[236:237]
	v_pk_mul_f32 v[44:45], v[44:45], v[236:237]
	v_pk_mul_f32 v[30:31], v[30:31], v[238:239]
	v_pk_mul_f32 v[46:47], v[46:47], v[238:239]

; __device__ __forceinline__ unsigned pk2(float lo, float hi) { f32x2_t v = {lo, hi}; bf16x2_t b = __builtin_convertvector(v, bf16x2_t); return __builtin_bit_cast(unsigned, b); }
; __device__ __forceinline__ float ex2(float x) { return __builtin_amdgcn_exp2f(x); }
; #define MFMA32(a, b, c) __builtin_amdgcn_mfma_f32_32x32x16_bf16((a), (b), (c), 0, 0, 0)
; template <bool MASK> __device__ __forceinline__ void sm_tile(f32x16& p0, f32x16& p1, float& mrun, float& lrun, f32x16& o0, f32x16& o1, LAS float* wsf, int kv0, int qpos, int q32, int hi) {
;     ...
;     float rs = 0.f;
; #pragma unroll
;     for (int r = 0; r < 16; ++r) { p0[r] = ex2(p0[r] - mrun); p1[r] = ex2(p1[r] - mrun); rs += p0[r] + p1[r]; }
;     rs += xhalf(rs, hi); lrun += rs;
; template <bool MASK> __device__ __forceinline__ void sm_iter(int var, SmState& st, const bf16x8 (&qr)[6], const LAS unsigned char* kb, const LAS unsigned char* vb, LAS float* wsf, int kv0, int qpos, int q32, int hi) {
;     ...
; #pragma unroll
;     for (int j = 0; j < 4; ++j) {
;         u32x4 pw;
;         if (j < 2) { const int r0 = 8 * (j & 1); pw.x = pk2(p0[r0], p0[r0 + 1]); pw.y = pk2(p0[r0 + 2], p0[r0 + 3]); pw.z = pk2(p0[r0 + 4], p0[r0 + 5]); pw.w = pk2(p0[r0 + 6], p0[r0 + 7]); }
;         else { const int r0 = 8 * (j & 1); pw.x = pk2(p1[r0], p1[r0 + 1]); pw.y = pk2(p1[r0 + 2], p1[r0 + 3]); pw.z = pk2(p1[r0 + 4], p1[r0 + 5]); pw.w = pk2(p1[r0 + 6], p1[r0 + 7]); }
;         const bf16x8 pa = __builtin_bit_cast(bf16x8, pw);
;         { const s16x4 lo = vlo[2 * j], hh = vhh[2 * j]; const bf16x8 vf = {lo[0], lo[1], lo[2], lo[3], hh[0], hh[1], hh[2], hh[3]}; st.o0 = MFMA32(pa, vf, st.o0); }
;         { const s16x4 lo = vlo[2 * j + 1], hh = vhh[2 * j + 1]; const bf16x8 vf = {lo[0], lo[1], lo[2], lo[3], hh[0], hh[1], hh[2], hh[3]}; st.o1 = MFMA32(pa, vf, st.o1); }
;     }
.Lm3_drain:
	v_exp_f32_e32 v48, v48
	v_exp_f32_e32 v49, v49
	v_exp_f32_e32 v50, v50
	v_add_f32_e32 v15, v48, v49
	v_exp_f32_e32 v51, v51
	v_cvt_pk_bf16_f32 v214, v48, v49
	v_exp_f32_e32 v52, v52
	v_add_f32_e32 v177, v50, v51
	v_exp_f32_e32 v53, v53
	v_cvt_pk_bf16_f32 v215, v50, v51
	v_exp_f32_e32 v54, v54
	v_add_f32_e32 v15, v15, v52
	v_exp_f32_e32 v55, v55
	v_add_f32_e32 v177, v177, v53
	v_exp_f32_e32 v56, v56
	v_cvt_pk_bf16_f32 v216, v52, v53
	v_exp_f32_e32 v57, v57
	v_add_f32_e32 v15, v15, v54
	v_exp_f32_e32 v58, v58
	v_add_f32_e32 v177, v177, v55
	v_exp_f32_e32 v59, v59
	v_cvt_pk_bf16_f32 v217, v54, v55
	v_exp_f32_e32 v60, v60
	v_add_f32_e32 v15, v15, v56
	v_exp_f32_e32 v61, v61
	v_add_f32_e32 v177, v177, v57
	v_exp_f32_e32 v62, v62
	v_cvt_pk_bf16_f32 v218, v56, v57
	v_exp_f32_e32 v63, v63
	v_add_f32_e32 v15, v15, v58
	v_add_f32_e32 v177, v177, v59
	v_cvt_pk_bf16_f32 v219, v58, v59
	v_add_f32_e32 v15, v15, v60
	v_add_f32_e32 v177, v177, v61
	v_cvt_pk_bf16_f32 v220, v60, v61
	v_add_f32_e32 v15, v15, v62
	v_add_f32_e32 v177, v177, v63
	v_cvt_pk_bf16_f32 v221, v62, v63
	v_add_f32_e32 v15, v15, v177
	v_add_f32_e32 v170, v170, v15
	s_nop 1
	v_mfma_f32_32x32x16_bf16 v[16:31], v[214:217], v[140:143], v[16:31]
	v_mfma_f32_32x32x16_bf16 v[32:47], v[214:217], v[144:147], v[32:47]
	v_mfma_f32_32x32x16_bf16 v[16:31], v[218:221], v[180:183], v[16:31]
	v_mfma_f32_32x32x16_bf16 v[32:47], v[218:221], v[184:187], v[32:47]
	v_mov_b32_e32 v15, v170
	v_mov_b32_e32 v177, v170
	v_sub_f32_e32 v171, 0, v198
	s_nop 0
	v_permlane32_swap_b32_e32 v15, v177
	v_add_f32_e32 v170, v15, v177
	s_branch .LBB0_58

; #define PG8_STAGE(bufoff, gbase, voff) do { _Pragma("unroll") for (int _i = 0; _i < 2; ++_i) \
;         __builtin_amdgcn_global_load_lds((const unsigned*)((const char*)(gbase) + (voff)[_i]), (PG8_LAS unsigned*)(lds + (bufoff) + ldsw + _i * 8192), 16, 0, 0); } while (0)
; #define PG8_LDA(dst, b, h) do { _Pragma("unroll") for (int m = 0; m < 4; ++m) _Pragma("unroll") for (int k = 0; k < 2; ++k) dst[m][k] = *(const PG8_LAS bf16x8*)(lds + PG8_SA(b, h) + aoff + m * 2048 + k * 1024); } while (0)
; #define PG8_LDB(dst, b, h) do { _Pragma("unroll") for (int n = 0; n < 2; ++n) _Pragma("unroll") for (int k = 0; k < 2; ++k) dst[n][k] = *(const PG8_LAS bf16x8*)(lds + PG8_SB(b, h) + boff + n * 2048 + k * 1024); } while (0)
; #define PG8_MMA(ai, bj, At, Bt) do { __builtin_amdgcn_s_setprio(1); _Pragma("unroll") for (int m = 0; m < 4; ++m) _Pragma("unroll") for (int n = 0; n < 2; ++n) _Pragma("unroll") for (int k = 0; k < 2; ++k) \
;         acc[ai][bj][m][n] = __builtin_amdgcn_mfma_f32_16x16x32_bf16(Bt[n][k], At[m][k], acc[ai][bj][m][n], 0, 0, 0); __builtin_amdgcn_s_setprio(0); } while (0)
; #define PG8_WAIT_V(n) asm volatile("s_waitcnt vmcnt(" #n ")" ::: "memory")
; #define PG8_WAIT_L(n) asm volatile("s_waitcnt lgkmcnt(" #n ")" ::: "memory")
; #define PG8_BAR __builtin_amdgcn_s_barrier()
; #define PG8_SCHED __builtin_amdgcn_sched_barrier(0)
; template <class Epi, class Sched, bool ALIGN_EPI = false, bool SP2 = false>
; __device__ __forceinline__ void gemm_phase(PG8_LAS unsigned char* lds, const Gemm g, const Sched& S, const Epi& E) {
;     ...
;             PG8_LDB(B0, 0, 0); PG8_LDB(B1, 0, 1); PG8_SCHED; PG8_LDA(At, 0, 0); PG8_STAGE(PG8_SA(1, 1), a1 + hstepA, voffA);
;             PG8_WAIT_V(8); PG8_WAIT_L(0); PG8_BAR; PG8_MMA(0, 0, At, B0); PG8_MMA(0, 1, At, B1); PG8_BAR; PG8_SCHED;
;             PG8_LDA(At, 0, 1); PG8_STAGE(PG8_SB(0, 0), b2, voffB); PG8_STAGE(PG8_SB(0, 1), b2 + hstep, voffB); PG8_STAGE(PG8_SA(0, 0), a2, voffA);
;             PG8_WAIT_V(8); PG8_WAIT_L(0); PG8_BAR; PG8_MMA(1, 0, At, B0); PG8_MMA(1, 1, At, B1); PG8_BAR; PG8_SCHED;
.LBB0_636:
	s_add_u32 s44, s42, 0xfffc0080
	s_addc_u32 s45, s43, -1
	s_add_i32 s60, 0, 0x10000
	s_cmp_eq_u32 s59, 12
	s_cselect_b32 s47, s19, s45
	s_cselect_b32 s46, s55, s44
	v_add_u32_e32 v150, s60, v151
	s_cselect_b32 s45, s11, s58
	s_cselect_b32 s44, s56, s57
	s_add_i32 s62, 0, 0x14000
	ds_read_b128 v[146:149], v150
	ds_read_b128 v[152:155], v150 offset:1024
	ds_read_b128 v[162:165], v150 offset:2048
	ds_read_b128 v[166:169], v150 offset:3072
	v_add_u32_e32 v150, s62, v151
	ds_read_b128 v[170:173], v150
	ds_read_b128 v[174:177], v150 offset:1024
	ds_read_b128 v[178:181], v150 offset:2048
	ds_read_b128 v[182:185], v150 offset:3072
	v_lshl_add_u64 v[158:159], s[42:43], 0, v[142:143]
	s_add_i32 m0, s16, 0xc000
	ds_read_b128 v[186:189], v161
	ds_read_b128 v[190:193], v161 offset:1024
	ds_read_b128 v[198:201], v161 offset:2048
	ds_read_b128 v[202:205], v161 offset:3072
	ds_read_b128 v[206:209], v161 offset:4096
	ds_read_b128 v[210:213], v161 offset:5120
	ds_read_b128 v[214:217], v161 offset:6144
	ds_read_b128 v[218:221], v161 offset:7168
	global_load_lds_dwordx4 v[158:159], off
	v_lshl_add_u64 v[158:159], s[42:43], 0, v[144:145]
	s_add_i32 m0, s16, 0xe000
	s_nop 0
	global_load_lds_dwordx4 v[158:159], off
	s_waitcnt vmcnt(8)
	s_waitcnt lgkmcnt(0)
	s_barrier
	s_setprio 1
	s_waitcnt lgkmcnt(0)
	v_mfma_f32_16x16x32_bf16 v[132:135], v[146:149], v[186:189], v[132:135]
	v_mfma_f32_16x16x32_bf16 v[128:131], v[162:165], v[186:189], v[128:131]
	v_mfma_f32_16x16x32_bf16 v[116:119], v[146:149], v[198:201], v[116:119]
	v_mfma_f32_16x16x32_bf16 v[112:115], v[162:165], v[198:201], v[112:115]
	v_mfma_f32_16x16x32_bf16 v[100:103], v[146:149], v[206:209], v[100:103]
	v_mfma_f32_16x16x32_bf16 v[96:99], v[162:165], v[206:209], v[96:99]
	v_mfma_f32_16x16x32_bf16 v[84:87], v[146:149], v[214:217], v[84:87]
	v_mfma_f32_16x16x32_bf16 v[74:77], v[162:165], v[214:217], v[74:77]
	v_mfma_f32_16x16x32_bf16 v[132:135], v[152:155], v[190:193], v[132:135]
	v_mfma_f32_16x16x32_bf16 v[128:131], v[166:169], v[190:193], v[128:131]
	v_mfma_f32_16x16x32_bf16 v[116:119], v[152:155], v[202:205], v[116:119]
	v_mfma_f32_16x16x32_bf16 v[112:115], v[166:169], v[202:205], v[112:115]
	v_mfma_f32_16x16x32_bf16 v[100:103], v[152:155], v[210:213], v[100:103]
	v_mfma_f32_16x16x32_bf16 v[96:99], v[166:169], v[210:213], v[96:99]
	v_mfma_f32_16x16x32_bf16 v[84:87], v[152:155], v[218:221], v[84:87]
	v_mfma_f32_16x16x32_bf16 v[74:77], v[166:169], v[218:221], v[74:77]
	s_setprio 0
	s_setprio 1
	v_mfma_f32_16x16x32_bf16 v[124:127], v[170:173], v[186:189], v[124:127]
	v_mfma_f32_16x16x32_bf16 v[120:123], v[178:181], v[186:189], v[120:123]
	v_mfma_f32_16x16x32_bf16 v[108:111], v[170:173], v[198:201], v[108:111]
	v_mfma_f32_16x16x32_bf16 v[104:107], v[178:181], v[198:201], v[104:107]
	v_mfma_f32_16x16x32_bf16 v[92:95], v[170:173], v[206:209], v[92:95]
	v_mfma_f32_16x16x32_bf16 v[88:91], v[178:181], v[206:209], v[88:91]
	v_mfma_f32_16x16x32_bf16 v[70:73], v[170:173], v[214:217], v[70:73]
	v_mfma_f32_16x16x32_bf16 v[66:69], v[178:181], v[214:217], v[66:69]
	v_mfma_f32_16x16x32_bf16 v[124:127], v[174:177], v[190:193], v[124:127]
	v_mfma_f32_16x16x32_bf16 v[120:123], v[182:185], v[190:193], v[120:123]
	v_mfma_f32_16x16x32_bf16 v[108:111], v[174:177], v[202:205], v[108:111]
	v_mfma_f32_16x16x32_bf16 v[104:107], v[182:185], v[202:205], v[104:107]
	v_mfma_f32_16x16x32_bf16 v[92:95], v[174:177], v[210:213], v[92:95]
	v_mfma_f32_16x16x32_bf16 v[88:91], v[182:185], v[210:213], v[88:91]
	v_mfma_f32_16x16x32_bf16 v[70:73], v[174:177], v[218:221], v[70:73]
	v_mfma_f32_16x16x32_bf16 v[66:69], v[182:185], v[218:221], v[66:69]
	s_setprio 0
	s_barrier
	s_add_i32 s60, s60, s0
	v_lshl_add_u64 v[158:159], s[44:45], 0, v[138:139]
	s_mov_b32 m0, s60
	ds_read_b128 v[186:189], v161 offset:16384
	ds_read_b128 v[190:193], v161 offset:17408
	ds_read_b128 v[198:201], v161 offset:18432
	ds_read_b128 v[202:205], v161 offset:19456
	ds_read_b128 v[206:209], v161 offset:20480
	ds_read_b128 v[210:213], v161 offset:21504
	ds_read_b128 v[214:217], v161 offset:22528
	ds_read_b128 v[218:221], v161 offset:23552
	global_load_lds_dwordx4 v[158:159], off
	s_add_i32 m0, s60, 0x2000
	s_add_u32 s60, s44, 0x40000
	v_lshl_add_u64 v[194:195], s[44:45], 0, v[78:79]
	s_addc_u32 s61, s45, 0
	s_add_i32 s62, s62, s0
	global_load_lds_dwordx4 v[194:195], off
	v_lshl_add_u64 v[222:223], s[60:61], 0, v[138:139]
	s_mov_b32 m0, s62
	v_lshl_add_u64 v[224:225], s[46:47], 0, v[136:137]
	global_load_lds_dwordx4 v[222:223], off
	v_lshl_add_u64 v[222:223], s[60:61], 0, v[78:79]
	s_add_i32 m0, s62, 0x2000
	s_nop 0
	global_load_lds_dwordx4 v[222:223], off
	v_lshl_add_u64 v[222:223], s[46:47], 0, v[140:141]
	s_mov_b32 m0, s16
	s_nop 0
	global_load_lds_dwordx4 v[222:223], off
	s_mov_b32 m0, s17
	s_nop 0
	global_load_lds_dwordx4 v[224:225], off
	s_waitcnt vmcnt(8)
	s_waitcnt lgkmcnt(0)
	s_barrier
; #define PG8_STAGE(bufoff, gbase, voff) do { _Pragma("unroll") for (int _i = 0; _i < 2; ++_i) \
;         __builtin_amdgcn_global_load_lds((const unsigned*)((const char*)(gbase) + (voff)[_i]), (PG8_LAS unsigned*)(lds + (bufoff) + ldsw + _i * 8192), 16, 0, 0); } while (0)
; #define PG8_LDA(dst, b, h) do { _Pragma("unroll") for (int m = 0; m < 4; ++m) _Pragma("unroll") for (int k = 0; k < 2; ++k) dst[m][k] = *(const PG8_LAS bf16x8*)(lds + PG8_SA(b, h) + aoff + m * 2048 + k * 1024); } while (0)
; #define PG8_LDB(dst, b, h) do { _Pragma("unroll") for (int n = 0; n < 2; ++n) _Pragma("unroll") for (int k = 0; k < 2; ++k) dst[n][k] = *(const PG8_LAS bf16x8*)(lds + PG8_SB(b, h) + boff + n * 2048 + k * 1024); } while (0)
; #define PG8_MMA(ai, bj, At, Bt) do { __builtin_amdgcn_s_setprio(1); _Pragma("unroll") for (int m = 0; m < 4; ++m) _Pragma("unroll") for (int n = 0; n < 2; ++n) _Pragma("unroll") for (int k = 0; k < 2; ++k) \
;         acc[ai][bj][m][n] = __builtin_amdgcn_mfma_f32_16x16x32_bf16(Bt[n][k], At[m][k], acc[ai][bj][m][n], 0, 0, 0); __builtin_amdgcn_s_setprio(0); } while (0)
; #define PG8_WAIT_V(n) asm volatile("s_waitcnt vmcnt(" #n ")" ::: "memory")
; #define PG8_WAIT_L(n) asm volatile("s_waitcnt lgkmcnt(" #n ")" ::: "memory")
; #define PG8_BAR __builtin_amdgcn_s_barrier()
; #define PG8_SCHED __builtin_amdgcn_sched_barrier(0)
; template <class Epi, class Sched, bool ALIGN_EPI = false, bool SP2 = false>
; __device__ __forceinline__ void gemm_phase(PG8_LAS unsigned char* lds, const Gemm g, const Sched& S, const Epi& E) {
;     ...
;             PG8_WAIT_V(8); PG8_WAIT_L(0); PG8_BAR; PG8_MMA(1, 0, At, B0); PG8_MMA(1, 1, At, B1); PG8_BAR; PG8_SCHED;
;             PG8_LDB(B0, 1, 0); PG8_LDB(B1, 1, 1); PG8_SCHED; PG8_LDA(At, 1, 0); PG8_STAGE(PG8_SA(0, 1), a2 + hstepA, voffA);
;             PG8_WAIT_V(8); PG8_WAIT_L(0); PG8_BAR; PG8_MMA(0, 0, At, B0); PG8_MMA(0, 1, At, B1); PG8_BAR; PG8_SCHED;
;             PG8_LDA(At, 1, 1); PG8_STAGE(PG8_SB(1, 0), b3, voffB); PG8_STAGE(PG8_SB(1, 1), b3 + hstep, voffB); PG8_STAGE(PG8_SA(1, 0), a3, voffA);
	s_setprio 1
	s_waitcnt lgkmcnt(0)
	v_mfma_f32_16x16x32_bf16 v[62:65], v[146:149], v[186:189], v[62:65]
	v_mfma_f32_16x16x32_bf16 v[58:61], v[162:165], v[186:189], v[58:61]
	v_mfma_f32_16x16x32_bf16 v[46:49], v[146:149], v[198:201], v[46:49]
	v_mfma_f32_16x16x32_bf16 v[42:45], v[162:165], v[198:201], v[42:45]
	v_mfma_f32_16x16x32_bf16 v[30:33], v[146:149], v[206:209], v[30:33]
	v_mfma_f32_16x16x32_bf16 v[26:29], v[162:165], v[206:209], v[26:29]
	v_mfma_f32_16x16x32_bf16 v[14:17], v[146:149], v[214:217], v[14:17]
	v_mfma_f32_16x16x32_bf16 v[10:13], v[162:165], v[214:217], v[10:13]
	v_mfma_f32_16x16x32_bf16 v[62:65], v[152:155], v[190:193], v[62:65]
	v_mfma_f32_16x16x32_bf16 v[58:61], v[166:169], v[190:193], v[58:61]
	v_mfma_f32_16x16x32_bf16 v[46:49], v[152:155], v[202:205], v[46:49]
	v_mfma_f32_16x16x32_bf16 v[42:45], v[166:169], v[202:205], v[42:45]
	v_mfma_f32_16x16x32_bf16 v[30:33], v[152:155], v[210:213], v[30:33]
	v_mfma_f32_16x16x32_bf16 v[26:29], v[166:169], v[210:213], v[26:29]
	v_mfma_f32_16x16x32_bf16 v[14:17], v[152:155], v[218:221], v[14:17]
	v_mfma_f32_16x16x32_bf16 v[10:13], v[166:169], v[218:221], v[10:13]
	s_setprio 0
	s_setprio 1
	v_mfma_f32_16x16x32_bf16 v[54:57], v[170:173], v[186:189], v[54:57]
	v_mfma_f32_16x16x32_bf16 v[50:53], v[178:181], v[186:189], v[50:53]
	v_mfma_f32_16x16x32_bf16 v[38:41], v[170:173], v[198:201], v[38:41]
	v_mfma_f32_16x16x32_bf16 v[34:37], v[178:181], v[198:201], v[34:37]
	v_mfma_f32_16x16x32_bf16 v[22:25], v[170:173], v[206:209], v[22:25]
	v_mfma_f32_16x16x32_bf16 v[18:21], v[178:181], v[206:209], v[18:21]
	v_mfma_f32_16x16x32_bf16 v[6:9], v[170:173], v[214:217], v[6:9]
	v_mfma_f32_16x16x32_bf16 v[2:5], v[178:181], v[214:217], v[2:5]
	v_mfma_f32_16x16x32_bf16 v[54:57], v[174:177], v[190:193], v[54:57]
	v_mfma_f32_16x16x32_bf16 v[50:53], v[182:185], v[190:193], v[50:53]
	v_mfma_f32_16x16x32_bf16 v[38:41], v[174:177], v[202:205], v[38:41]
	v_mfma_f32_16x16x32_bf16 v[34:37], v[182:185], v[202:205], v[34:37]
	v_mfma_f32_16x16x32_bf16 v[22:25], v[174:177], v[210:213], v[22:25]
	v_mfma_f32_16x16x32_bf16 v[18:21], v[182:185], v[210:213], v[18:21]
	v_mfma_f32_16x16x32_bf16 v[6:9], v[174:177], v[218:221], v[6:9]
	v_mfma_f32_16x16x32_bf16 v[2:5], v[182:185], v[218:221], v[2:5]
	s_setprio 0
	s_barrier
	s_add_i32 s60, 0, 0x18000
	v_add_u32_e32 v150, s60, v151
	s_add_i32 s61, 0, 0x1c000
	ds_read_b128 v[146:149], v150
	ds_read_b128 v[152:155], v150 offset:1024
	ds_read_b128 v[162:165], v150 offset:2048
	ds_read_b128 v[166:169], v150 offset:3072
	v_add_u32_e32 v150, s61, v151
	ds_read_b128 v[170:173], v150
	ds_read_b128 v[174:177], v150 offset:1024
	ds_read_b128 v[178:181], v150 offset:2048
	ds_read_b128 v[182:185], v150 offset:3072
	s_add_u32 s46, s46, 0x40000
	s_addc_u32 s47, s47, 0
	s_mov_b32 m0, s37
	v_lshl_add_u64 v[226:227], s[46:47], 0, v[140:141]
	ds_read_b128 v[186:189], v161 offset:32768
	ds_read_b128 v[190:193], v161 offset:33792
	ds_read_b128 v[198:201], v161 offset:34816
	ds_read_b128 v[202:205], v161 offset:35840
	ds_read_b128 v[206:209], v161 offset:36864
	ds_read_b128 v[210:213], v161 offset:37888
	ds_read_b128 v[214:217], v161 offset:38912
	ds_read_b128 v[218:221], v161 offset:39936
	global_load_lds_dwordx4 v[226:227], off
	v_lshl_add_u64 v[226:227], s[46:47], 0, v[136:137]
	s_mov_b32 m0, s48
	s_nop 0
	global_load_lds_dwordx4 v[226:227], off
	s_waitcnt vmcnt(8)
	s_waitcnt lgkmcnt(0)
	s_barrier
	s_setprio 1
	s_waitcnt lgkmcnt(0)
	v_mfma_f32_16x16x32_bf16 v[132:135], v[146:149], v[186:189], v[132:135]
	v_mfma_f32_16x16x32_bf16 v[128:131], v[162:165], v[186:189], v[128:131]
	v_mfma_f32_16x16x32_bf16 v[116:119], v[146:149], v[198:201], v[116:119]
	v_mfma_f32_16x16x32_bf16 v[112:115], v[162:165], v[198:201], v[112:115]
	v_mfma_f32_16x16x32_bf16 v[100:103], v[146:149], v[206:209], v[100:103]
	v_mfma_f32_16x16x32_bf16 v[96:99], v[162:165], v[206:209], v[96:99]
	v_mfma_f32_16x16x32_bf16 v[84:87], v[146:149], v[214:217], v[84:87]
	v_mfma_f32_16x16x32_bf16 v[74:77], v[162:165], v[214:217], v[74:77]
	v_mfma_f32_16x16x32_bf16 v[132:135], v[152:155], v[190:193], v[132:135]
	v_mfma_f32_16x16x32_bf16 v[128:131], v[166:169], v[190:193], v[128:131]
	v_mfma_f32_16x16x32_bf16 v[116:119], v[152:155], v[202:205], v[116:119]
	v_mfma_f32_16x16x32_bf16 v[112:115], v[166:169], v[202:205], v[112:115]
	v_mfma_f32_16x16x32_bf16 v[100:103], v[152:155], v[210:213], v[100:103]
	v_mfma_f32_16x16x32_bf16 v[96:99], v[166:169], v[210:213], v[96:99]
	v_mfma_f32_16x16x32_bf16 v[84:87], v[152:155], v[218:221], v[84:87]
	v_mfma_f32_16x16x32_bf16 v[74:77], v[166:169], v[218:221], v[74:77]
	s_setprio 0
	s_setprio 1
	v_mfma_f32_16x16x32_bf16 v[124:127], v[170:173], v[186:189], v[124:127]
	v_mfma_f32_16x16x32_bf16 v[120:123], v[178:181], v[186:189], v[120:123]
	v_mfma_f32_16x16x32_bf16 v[108:111], v[170:173], v[198:201], v[108:111]
	v_mfma_f32_16x16x32_bf16 v[104:107], v[178:181], v[198:201], v[104:107]
	v_mfma_f32_16x16x32_bf16 v[92:95], v[170:173], v[206:209], v[92:95]
	v_mfma_f32_16x16x32_bf16 v[88:91], v[178:181], v[206:209], v[88:91]
	v_mfma_f32_16x16x32_bf16 v[70:73], v[170:173], v[214:217], v[70:73]
	v_mfma_f32_16x16x32_bf16 v[66:69], v[178:181], v[214:217], v[66:69]
	v_mfma_f32_16x16x32_bf16 v[124:127], v[174:177], v[190:193], v[124:127]
	v_mfma_f32_16x16x32_bf16 v[120:123], v[182:185], v[190:193], v[120:123]
	v_mfma_f32_16x16x32_bf16 v[108:111], v[174:177], v[202:205], v[108:111]
	v_mfma_f32_16x16x32_bf16 v[104:107], v[182:185], v[202:205], v[104:107]
	v_mfma_f32_16x16x32_bf16 v[92:95], v[174:177], v[210:213], v[92:95]
	v_mfma_f32_16x16x32_bf16 v[88:91], v[182:185], v[210:213], v[88:91]
	v_mfma_f32_16x16x32_bf16 v[70:73], v[174:177], v[218:221], v[70:73]
	v_mfma_f32_16x16x32_bf16 v[66:69], v[182:185], v[218:221], v[66:69]
	s_setprio 0
	s_barrier
; #define PG8_WAIT_V(n) asm volatile("s_waitcnt vmcnt(" #n ")" ::: "memory")
; #define PG8_WAIT_L(n) asm volatile("s_waitcnt lgkmcnt(" #n ")" ::: "memory")
; __device__ __forceinline__ void rstd8(const float* ssq, int row0, float (&rs)[2][4]) {
;     f32x4 q[2][4];
; #pragma unroll
;     for (int ai = 0; ai < 2; ++ai)
; #pragma unroll
;         for (int m = 0; m < 4; ++m) q[ai][m] = *(const f32x4*)(ssq + (size_t)(row0 + ai * HALF + m * 16) * 4);
; template <class Epi, class Sched, bool ALIGN_EPI = false, bool SP2 = false>
; __device__ __forceinline__ void gemm_phase(PG8_LAS unsigned char* lds, const Gemm g, const Sched& S, const Epi& E) {
;     ...
;             PG8_WAIT_V(8); PG8_WAIT_L(0); PG8_BAR; PG8_MMA(0, 0, At, B0); PG8_MMA(0, 1, At, B1); PG8_BAR; PG8_SCHED;
;             PG8_LDA(At, 1, 1); PG8_STAGE(PG8_SB(1, 0), b3, voffB); PG8_STAGE(PG8_SB(1, 1), b3 + hstep, voffB); PG8_STAGE(PG8_SA(1, 0), a3, voffA);
;             PG8_WAIT_V(8); PG8_WAIT_L(0); PG8_BAR; PG8_MMA(1, 0, At, B0); PG8_MMA(1, 1, At, B1); PG8_BAR; PG8_SCHED;
;             } else {
;             PG8_LDB(B0, 0, 0); PG8_SCHED; PG8_LDA(At, 0, 0); PG8_STAGE(PG8_SA(1, 1), a1 + hstepA, voffA);
;             PG8_WAIT_L(8); PG8_BAR; PG8_WAIT_L(0); PG8_MMA(0, 0, At, B0); PG8_BAR; PG8_SCHED;
;             PG8_LDB(B1, 0, 1); PG8_STAGE(PG8_SB(0, 0), b2, voffB);
;             PG8_BAR; PG8_WAIT_L(0); PG8_MMA(0, 1, At, B1); PG8_BAR;
;             PG8_LDA(At, 0, 1); PG8_STAGE(PG8_SA(0, 0), a2, voffA);
;             PG8_BAR; PG8_WAIT_L(0); PG8_MMA(1, 0, At, B0); PG8_BAR; PG8_SCHED;
;             PG8_STAGE(PG8_SB(0, 1), b2 + hstep, voffB);
;             PG8_WAIT_V(6); PG8_BAR; PG8_MMA(1, 1, At, B1); PG8_BAR;
;             PG8_LDB(B0, 1, 0); PG8_SCHED; PG8_LDA(At, 1, 0); PG8_STAGE(PG8_SA(0, 1), a2 + hstepA, voffA);
;             PG8_WAIT_L(8); PG8_BAR; PG8_WAIT_L(0); PG8_MMA(0, 0, At, B0); PG8_BAR; PG8_SCHED;
;             PG8_LDB(B1, 1, 1); PG8_STAGE(PG8_SB(1, 0), b3, voffB);
;             PG8_BAR; PG8_WAIT_L(0); PG8_MMA(0, 1, At, B1); PG8_BAR;
;             PG8_LDA(At, 1, 1); PG8_STAGE(PG8_SA(1, 0), a3, voffA);
;             PG8_BAR; PG8_WAIT_L(0); PG8_MMA(1, 0, At, B0); PG8_BAR; PG8_SCHED;
;             PG8_STAGE(PG8_SB(1, 1), b3 + hstep, voffB);
;             PG8_WAIT_V(6); PG8_BAR; PG8_MMA(1, 1, At, B1); PG8_BAR;
;             }
;         }
;         if constexpr (ALIGN_EPI) { if (wr == 0) PG8_BAR; }
	s_add_i32 s46, s60, s0
	v_lshl_add_u64 v[158:159], v[158:159], 0, s[26:27]
	s_mov_b32 m0, s46
	ds_read_b128 v[186:189], v161 offset:49152
	ds_read_b128 v[190:193], v161 offset:50176
	ds_read_b128 v[198:201], v161 offset:51200
	ds_read_b128 v[202:205], v161 offset:52224
	ds_read_b128 v[206:209], v161 offset:53248
	ds_read_b128 v[210:213], v161 offset:54272
	ds_read_b128 v[214:217], v161 offset:55296
	ds_read_b128 v[218:221], v161 offset:56320
	global_load_lds_dwordx4 v[158:159], off
	s_add_i32 m0, s46, 0x2000
	s_add_u32 s44, s44, 0x40080
	v_lshl_add_u64 v[158:159], v[194:195], 0, s[26:27]
	s_addc_u32 s45, s45, 0
	s_add_i32 s46, s61, s0
	global_load_lds_dwordx4 v[158:159], off
	v_lshl_add_u64 v[158:159], s[44:45], 0, v[138:139]
	s_mov_b32 m0, s46
	s_nop 0
	global_load_lds_dwordx4 v[158:159], off
	v_lshl_add_u64 v[158:159], s[44:45], 0, v[78:79]
	s_add_i32 m0, s46, 0x2000
	s_nop 0
	global_load_lds_dwordx4 v[158:159], off
	v_lshl_add_u64 v[158:159], v[222:223], 0, s[26:27]
	s_mov_b32 m0, s49
	s_nop 0
	global_load_lds_dwordx4 v[158:159], off
	v_lshl_add_u64 v[158:159], v[224:225], 0, s[26:27]
	s_mov_b32 m0, s53
	s_nop 0
	global_load_lds_dwordx4 v[158:159], off
	s_waitcnt vmcnt(8)
	s_waitcnt lgkmcnt(0)
	s_barrier
	s_setprio 1
	s_waitcnt lgkmcnt(0)
	v_mfma_f32_16x16x32_bf16 v[62:65], v[146:149], v[186:189], v[62:65]
	v_mfma_f32_16x16x32_bf16 v[58:61], v[162:165], v[186:189], v[58:61]
	v_mfma_f32_16x16x32_bf16 v[46:49], v[146:149], v[198:201], v[46:49]
	v_mfma_f32_16x16x32_bf16 v[42:45], v[162:165], v[198:201], v[42:45]
	v_mfma_f32_16x16x32_bf16 v[30:33], v[146:149], v[206:209], v[30:33]
	v_mfma_f32_16x16x32_bf16 v[26:29], v[162:165], v[206:209], v[26:29]
	v_mfma_f32_16x16x32_bf16 v[14:17], v[146:149], v[214:217], v[14:17]
	v_mfma_f32_16x16x32_bf16 v[10:13], v[162:165], v[214:217], v[10:13]
	v_mfma_f32_16x16x32_bf16 v[62:65], v[152:155], v[190:193], v[62:65]
	v_mfma_f32_16x16x32_bf16 v[58:61], v[166:169], v[190:193], v[58:61]
	v_mfma_f32_16x16x32_bf16 v[46:49], v[152:155], v[202:205], v[46:49]
	v_mfma_f32_16x16x32_bf16 v[42:45], v[166:169], v[202:205], v[42:45]
	v_mfma_f32_16x16x32_bf16 v[30:33], v[152:155], v[210:213], v[30:33]
	v_mfma_f32_16x16x32_bf16 v[26:29], v[166:169], v[210:213], v[26:29]
	v_mfma_f32_16x16x32_bf16 v[14:17], v[152:155], v[218:221], v[14:17]
	v_mfma_f32_16x16x32_bf16 v[10:13], v[166:169], v[218:221], v[10:13]
	s_setprio 0
	s_setprio 1
	v_mfma_f32_16x16x32_bf16 v[54:57], v[170:173], v[186:189], v[54:57]
	v_mfma_f32_16x16x32_bf16 v[50:53], v[178:181], v[186:189], v[50:53]
	v_mfma_f32_16x16x32_bf16 v[38:41], v[170:173], v[198:201], v[38:41]
	v_mfma_f32_16x16x32_bf16 v[34:37], v[178:181], v[198:201], v[34:37]
	v_mfma_f32_16x16x32_bf16 v[22:25], v[170:173], v[206:209], v[22:25]
	v_mfma_f32_16x16x32_bf16 v[18:21], v[178:181], v[206:209], v[18:21]
	v_mfma_f32_16x16x32_bf16 v[6:9], v[170:173], v[214:217], v[6:9]
	v_mfma_f32_16x16x32_bf16 v[2:5], v[178:181], v[214:217], v[2:5]
	v_mfma_f32_16x16x32_bf16 v[54:57], v[174:177], v[190:193], v[54:57]
	v_mfma_f32_16x16x32_bf16 v[50:53], v[182:185], v[190:193], v[50:53]
	v_mfma_f32_16x16x32_bf16 v[38:41], v[174:177], v[202:205], v[38:41]
	v_mfma_f32_16x16x32_bf16 v[34:37], v[182:185], v[202:205], v[34:37]
	v_mfma_f32_16x16x32_bf16 v[22:25], v[174:177], v[210:213], v[22:25]
	v_mfma_f32_16x16x32_bf16 v[18:21], v[182:185], v[210:213], v[18:21]
	v_mfma_f32_16x16x32_bf16 v[6:9], v[174:177], v[218:221], v[6:9]
	v_mfma_f32_16x16x32_bf16 v[2:5], v[182:185], v[218:221], v[2:5]
	s_setprio 0
	s_barrier
	s_add_i32 s59, s59, 2
	s_add_u32 s42, s42, 0x100
	s_addc_u32 s43, s43, 0
	s_add_u32 s57, s57, 0x100
	s_addc_u32 s58, s58, 0
	s_cmp_gt_u32 s59, 13
	s_cbranch_scc0 .LBB0_636
	v_lshl_add_u32 v154, s5, 8, v1
	v_ashrrev_i32_e32 v155, 31, v154
	v_lshl_add_u64 v[146:147], v[154:155], 4, s[28:29]
	v_or_b32_e32 v174, 16, v154
	global_load_dwordx4 v[180:183], v[146:147], off
	v_ashrrev_i32_e32 v175, 31, v174
	v_lshl_add_u64 v[146:147], v[174:175], 4, s[28:29]
	v_or_b32_e32 v170, 32, v154
	global_load_dwordx4 v[184:187], v[146:147], off
	v_ashrrev_i32_e32 v171, 31, v170
	v_lshl_add_u64 v[146:147], v[170:171], 4, s[28:29]
	v_or_b32_e32 v166, 48, v154
	global_load_dwordx4 v[188:191], v[146:147], off
	v_ashrrev_i32_e32 v167, 31, v166
	v_lshl_add_u64 v[146:147], v[166:167], 4, s[28:29]
	v_add_u32_e32 v162, 0x80, v154
	global_load_dwordx4 v[192:195], v[146:147], off
	v_ashrrev_i32_e32 v163, 31, v162
	v_lshl_add_u64 v[146:147], v[162:163], 4, s[28:29]
	v_add_u32_e32 v158, 0x90, v154
	global_load_dwordx4 v[198:201], v[146:147], off
	v_ashrrev_i32_e32 v159, 31, v158
	v_add_u32_e32 v148, 0xa0, v154
	v_lshl_add_u64 v[146:147], v[158:159], 4, s[28:29]
	v_ashrrev_i32_e32 v149, 31, v148
	global_load_dwordx4 v[202:205], v[146:147], off
	v_lshl_add_u64 v[146:147], v[148:149], 4, s[28:29]
	global_load_dwordx4 v[206:209], v[146:147], off
	v_add_u32_e32 v146, 0xb0, v154
	v_ashrrev_i32_e32 v147, 31, v146
	v_lshl_add_u64 v[152:153], v[146:147], 4, s[28:29]
	global_load_dwordx4 v[210:213], v[152:153], off
	v_mul_f32_e32 v124, v132, v124
	v_mul_f32_e32 v125, v133, v125
	v_mul_f32_e32 v126, v134, v126
	v_mul_f32_e32 v127, v135, v127
	v_mul_f32_e32 v120, v128, v120
	v_mul_f32_e32 v121, v129, v121
	v_mul_f32_e32 v122, v130, v122
	v_mul_f32_e32 v123, v131, v123
	v_mul_f32_e32 v108, v116, v108
	v_mul_f32_e32 v109, v117, v109
	v_mul_f32_e32 v110, v118, v110
	v_mul_f32_e32 v111, v119, v111
	v_mul_f32_e32 v104, v112, v104
	v_mul_f32_e32 v105, v113, v105
	v_mul_f32_e32 v106, v114, v106
	v_mul_f32_e32 v107, v115, v107
	v_mul_f32_e32 v92, v100, v92
	v_mul_f32_e32 v93, v101, v93
	v_mul_f32_e32 v94, v102, v94
	v_mul_f32_e32 v95, v103, v95
	v_mul_f32_e32 v88, v96, v88
	v_mul_f32_e32 v89, v97, v89
	v_mul_f32_e32 v90, v98, v90
	v_mul_f32_e32 v91, v99, v91
	v_mul_f32_e32 v70, v84, v70
	v_mul_f32_e32 v71, v85, v71
	v_mul_f32_e32 v72, v86, v72
	v_mul_f32_e32 v73, v87, v73
	v_mul_f32_e32 v66, v74, v66
	v_mul_f32_e32 v67, v75, v67
	v_mul_f32_e32 v68, v76, v68
	v_mul_f32_e32 v69, v77, v69
	v_mul_f32_e32 v54, v62, v54
	v_mul_f32_e32 v55, v63, v55
	v_mul_f32_e32 v56, v64, v56
	v_mul_f32_e32 v57, v65, v57
	v_mul_f32_e32 v50, v58, v50
	v_mul_f32_e32 v51, v59, v51
	v_mul_f32_e32 v52, v60, v52
	v_mul_f32_e32 v53, v61, v53
	v_mul_f32_e32 v38, v46, v38
	v_mul_f32_e32 v39, v47, v39
	v_mul_f32_e32 v40, v48, v40
	v_mul_f32_e32 v41, v49, v41
	v_mul_f32_e32 v34, v42, v34
	v_mul_f32_e32 v35, v43, v35
	v_mul_f32_e32 v36, v44, v36
	v_mul_f32_e32 v37, v45, v37
	v_mul_f32_e32 v22, v30, v22
	v_mul_f32_e32 v23, v31, v23
	v_mul_f32_e32 v24, v32, v24
	v_mul_f32_e32 v25, v33, v25
	v_mul_f32_e32 v18, v26, v18
	v_mul_f32_e32 v19, v27, v19
	v_mul_f32_e32 v20, v28, v20
	v_mul_f32_e32 v21, v29, v21
	v_mul_f32_e32 v6, v14, v6
	v_mul_f32_e32 v7, v15, v7
	v_mul_f32_e32 v8, v16, v8
	v_mul_f32_e32 v9, v17, v9
	v_mul_f32_e32 v2, v10, v2
	v_mul_f32_e32 v3, v11, v3
	v_mul_f32_e32 v4, v12, v4
	v_mul_f32_e32 v5, v13, v5
	s_and_b64 vcc, exec, s[8:9]
	s_cbranch_vccz .LBB0_639
	s_barrier
; __device__ __forceinline__ unsigned cvt_pk_bf16(float lo, float hi) { unsigned r; asm volatile("v_cvt_pk_bf16_f32 %0, %1, %2" : "=v"(r) : "v"(lo), "v"(hi)); return r; }
; __device__ __forceinline__ float silu_mul(float g, float u) { const float e = __builtin_amdgcn_exp2f(g * -1.4426950408889634f); return g * u * __builtin_amdgcn_rcpf(1.0f + e); }
; __device__ __forceinline__ void rstd8(const float* ssq, int row0, float (&rs)[2][4]) {
;     f32x4 q[2][4];
; #pragma unroll
;     for (int ai = 0; ai < 2; ++ai)
; #pragma unroll
;         for (int m = 0; m < 4; ++m) q[ai][m] = *(const f32x4*)(ssq + (size_t)(row0 + ai * HALF + m * 16) * 4);
; #pragma unroll
;     for (int ai = 0; ai < 2; ++ai)
; #pragma unroll
;         for (int m = 0; m < 4; ++m) rs[ai][m] = __builtin_amdgcn_rsqf(((q[ai][m][0] + q[ai][m][1]) + (q[ai][m][2] + q[ai][m][3])) * (1.0f / 1024.0f) + NORM_EPS);
;     __device__ __forceinline__ void operator()(const f32x4 (&acc)[2][2][4][2], const Unit& u, int wr, int wc, int fr, int fq) const {
;     ...
;         for (int ai = 0; ai < 2; ++ai)
; #pragma unroll
;             for (int m = 0; m < 4; ++m) { const int row = row0 + ai * HALF + m * 16; bf16_t* rowp = O + (size_t)row * ldc + col0; const float rs = rs8[ai][m];
;                 const f32x4 g0 = acc[ai][0][m][0] * rs, g1 = acc[ai][0][m][1] * rs, u0 = acc[ai][1][m][0] * rs, u1 = acc[ai][1][m][1] * rs;
;                 u32x4 w; w.x = cvt_pk_bf16(silu_mul(g0[0], u0[0]), silu_mul(g0[1], u0[1])); w.y = cvt_pk_bf16(silu_mul(g0[2], u0[2]), silu_mul(g0[3], u0[3]));
;                 w.z = cvt_pk_bf16(silu_mul(g1[0], u1[0]), silu_mul(g1[1], u1[1])); w.w = cvt_pk_bf16(silu_mul(g1[2], u1[2]), silu_mul(g1[3], u1[3]));
;                 *(u32x4*)rowp = w; }
.LBB0_639:
	v_lshl_or_b32 v178, s4, 7, v157
	v_readlane_b32 s4, v254, 32
	v_readlane_b32 s5, v254, 33
	v_ashrrev_i32_e32 v179, 31, v178
	s_movk_i32 s11, 0x1600
	s_mov_b64 s[42:43], -1
	s_andn2_b64 vcc, exec, s[40:41]
	s_waitcnt vmcnt(0)
	v_add_f32_e32 v180, v180, v181
	v_add_f32_e32 v182, v182, v183
	v_add_f32_e32 v184, v184, v185
	v_add_f32_e32 v186, v186, v187
	v_add_f32_e32 v188, v188, v189
	v_add_f32_e32 v190, v190, v191
	v_add_f32_e32 v192, v192, v193
	v_add_f32_e32 v194, v194, v195
	v_add_f32_e32 v198, v198, v199
	v_add_f32_e32 v200, v200, v201
	v_add_f32_e32 v202, v202, v203
	v_add_f32_e32 v204, v204, v205
	v_add_f32_e32 v206, v206, v207
	v_add_f32_e32 v208, v208, v209
	v_add_f32_e32 v210, v210, v211
	v_add_f32_e32 v212, v212, v213
	v_add_f32_e32 v180, v180, v182
	v_add_f32_e32 v184, v184, v186
	v_add_f32_e32 v188, v188, v190
	v_add_f32_e32 v192, v192, v194
	v_add_f32_e32 v198, v198, v200
	v_add_f32_e32 v202, v202, v204
	v_add_f32_e32 v206, v206, v208
	v_add_f32_e32 v210, v210, v212
	v_fmamk_f32 v180, v180, 0x3a800000, v229
	v_fmamk_f32 v184, v184, 0x3a800000, v229
	v_fmamk_f32 v188, v188, 0x3a800000, v229
	v_fmamk_f32 v192, v192, 0x3a800000, v229
	v_fmamk_f32 v198, v198, 0x3a800000, v229
	v_fmamk_f32 v202, v202, 0x3a800000, v229
	v_fmamk_f32 v206, v206, 0x3a800000, v229
	v_fmamk_f32 v210, v210, 0x3a800000, v229
	v_rsq_f32_e32 v181, v180
	v_rsq_f32_e32 v185, v184
	v_rsq_f32_e32 v189, v188
	v_rsq_f32_e32 v193, v192
	v_rsq_f32_e32 v199, v198
	v_rsq_f32_e32 v203, v202
	v_rsq_f32_e32 v207, v206
	v_rsq_f32_e32 v211, v210
	v_mov_b64_e32 v[152:153], s[4:5]
	v_mad_i64_i32 v[182:183], s[4:5], v154, s11, v[152:153]
	v_lshlrev_b64 v[154:155], 1, v[178:179]
	v_mul_f32_e32 v181, 0xbfb8aa3b, v181
	v_mul_f32_e32 v185, 0xbfb8aa3b, v185
	v_mul_f32_e32 v189, 0xbfb8aa3b, v189
	v_mul_f32_e32 v193, 0xbfb8aa3b, v193
	v_mul_f32_e32 v199, 0xbfb8aa3b, v199
	v_mul_f32_e32 v203, 0xbfb8aa3b, v203
	v_mul_f32_e32 v207, 0xbfb8aa3b, v207
	v_mul_f32_e32 v211, 0xbfb8aa3b, v211
	v_mad_i64_i32 v[186:187], s[4:5], v174, s11, v[152:153]
	v_mad_i64_i32 v[190:191], s[4:5], v170, s11, v[152:153]
	v_mad_i64_i32 v[194:195], s[4:5], v166, s11, v[152:153]
	v_mad_i64_i32 v[200:201], s[4:5], v162, s11, v[152:153]
	v_mad_i64_i32 v[204:205], s[4:5], v158, s11, v[152:153]
	v_mad_i64_i32 v[208:209], s[4:5], v148, s11, v[152:153]
	v_mad_i64_i32 v[212:213], s[4:5], v146, s11, v[152:153]
	v_lshl_add_u64 v[182:183], v[182:183], 0, v[154:155]
	v_lshl_add_u64 v[186:187], v[186:187], 0, v[154:155]
	v_lshl_add_u64 v[190:191], v[190:191], 0, v[154:155]
	v_lshl_add_u64 v[194:195], v[194:195], 0, v[154:155]
	v_lshl_add_u64 v[200:201], v[200:201], 0, v[154:155]
	v_lshl_add_u64 v[204:205], v[204:205], 0, v[154:155]
	v_lshl_add_u64 v[208:209], v[208:209], 0, v[154:155]
	v_lshl_add_u64 v[212:213], v[212:213], 0, v[154:155]
	v_mul_f32_e32 v132, v181, v132
	v_exp_f32_e32 v132, v132
	v_mul_f32_e32 v133, v181, v133
	v_exp_f32_e32 v133, v133
	v_fma_f32 v132, v132, v180, v180
	v_rcp_f32_e32 v132, v132
	v_mul_f32_e32 v134, v181, v134
	v_exp_f32_e32 v134, v134
	v_fma_f32 v133, v133, v180, v180
	v_rcp_f32_e32 v133, v133
	v_mul_f32_e32 v135, v181, v135
	v_mul_f32_e32 v124, v124, v132
	v_exp_f32_e32 v135, v135
	v_fma_f32 v134, v134, v180, v180
	v_rcp_f32_e32 v134, v134
	v_mul_f32_e32 v128, v181, v128
	v_mul_f32_e32 v125, v125, v133
	v_exp_f32_e32 v128, v128
	v_fma_f32 v135, v135, v180, v180
	v_rcp_f32_e32 v135, v135
	v_mul_f32_e32 v129, v181, v129
	v_mul_f32_e32 v126, v126, v134
	v_exp_f32_e32 v129, v129
	v_fma_f32 v128, v128, v180, v180
	v_rcp_f32_e32 v128, v128
	v_mul_f32_e32 v130, v181, v130
	v_mul_f32_e32 v127, v127, v135
	v_exp_f32_e32 v130, v130
	v_fma_f32 v129, v129, v180, v180
	v_rcp_f32_e32 v129, v129
	v_mul_f32_e32 v131, v181, v131
	v_mul_f32_e32 v120, v120, v128
	v_exp_f32_e32 v131, v131
	v_fma_f32 v130, v130, v180, v180
	v_rcp_f32_e32 v130, v130
	v_mul_f32_e32 v116, v185, v116
	v_mul_f32_e32 v121, v121, v129
	v_exp_f32_e32 v116, v116
	v_fma_f32 v131, v131, v180, v180
	v_rcp_f32_e32 v131, v131
	v_mul_f32_e32 v117, v185, v117
	v_mul_f32_e32 v122, v122, v130
	v_exp_f32_e32 v117, v117
	v_fma_f32 v116, v116, v184, v184
	v_rcp_f32_e32 v116, v116
	v_mul_f32_e32 v118, v185, v118
	v_mul_f32_e32 v123, v123, v131
	v_cvt_pk_bf16_f32 v123, v122, v123
	v_cvt_pk_bf16_f32 v122, v120, v121
	v_cvt_pk_bf16_f32 v120, v124, v125
	v_cvt_pk_bf16_f32 v121, v126, v127
	global_store_dwordx4 v[182:183], v[120:123], off
	v_exp_f32_e32 v118, v118
	v_fma_f32 v117, v117, v184, v184
	v_rcp_f32_e32 v117, v117
	v_mul_f32_e32 v119, v185, v119
	v_mul_f32_e32 v108, v108, v116
	v_exp_f32_e32 v119, v119
	v_fma_f32 v118, v118, v184, v184
	v_rcp_f32_e32 v118, v118
	v_mul_f32_e32 v112, v185, v112
	v_mul_f32_e32 v109, v109, v117
	v_exp_f32_e32 v112, v112
	v_fma_f32 v119, v119, v184, v184
	v_rcp_f32_e32 v119, v119
	v_mul_f32_e32 v113, v185, v113
	v_mul_f32_e32 v110, v110, v118
	v_exp_f32_e32 v113, v113
	v_fma_f32 v112, v112, v184, v184
	v_rcp_f32_e32 v112, v112
	v_mul_f32_e32 v114, v185, v114
	v_mul_f32_e32 v111, v111, v119
	v_exp_f32_e32 v114, v114
	v_fma_f32 v113, v113, v184, v184
	v_rcp_f32_e32 v113, v113
	v_mul_f32_e32 v115, v185, v115
	v_mul_f32_e32 v104, v104, v112
	v_exp_f32_e32 v115, v115
	v_fma_f32 v114, v114, v184, v184
	v_rcp_f32_e32 v114, v114
	v_mul_f32_e32 v100, v189, v100
	v_mul_f32_e32 v105, v105, v113
	v_exp_f32_e32 v100, v100
	v_fma_f32 v115, v115, v184, v184
	v_rcp_f32_e32 v115, v115
	v_mul_f32_e32 v101, v189, v101
	v_mul_f32_e32 v106, v106, v114
	v_exp_f32_e32 v101, v101
	v_fma_f32 v100, v100, v188, v188
	v_rcp_f32_e32 v100, v100
	v_mul_f32_e32 v102, v189, v102
	v_mul_f32_e32 v107, v107, v115
	v_cvt_pk_bf16_f32 v107, v106, v107
; __device__ __forceinline__ unsigned cvt_pk_bf16(float lo, float hi) { unsigned r; asm volatile("v_cvt_pk_bf16_f32 %0, %1, %2" : "=v"(r) : "v"(lo), "v"(hi)); return r; }
; __device__ __forceinline__ float silu_mul(float g, float u) { const float e = __builtin_amdgcn_exp2f(g * -1.4426950408889634f); return g * u * __builtin_amdgcn_rcpf(1.0f + e); }
;     __device__ __forceinline__ void operator()(const f32x4 (&acc)[2][2][4][2], const Unit& u, int wr, int wc, int fr, int fq) const {
;     ...
;         for (int ai = 0; ai < 2; ++ai)
; #pragma unroll
;             for (int m = 0; m < 4; ++m) { const int row = row0 + ai * HALF + m * 16; bf16_t* rowp = O + (size_t)row * ldc + col0; const float rs = rs8[ai][m];
;                 const f32x4 g0 = acc[ai][0][m][0] * rs, g1 = acc[ai][0][m][1] * rs, u0 = acc[ai][1][m][0] * rs, u1 = acc[ai][1][m][1] * rs;
;                 u32x4 w; w.x = cvt_pk_bf16(silu_mul(g0[0], u0[0]), silu_mul(g0[1], u0[1])); w.y = cvt_pk_bf16(silu_mul(g0[2], u0[2]), silu_mul(g0[3], u0[3]));
;                 w.z = cvt_pk_bf16(silu_mul(g1[0], u1[0]), silu_mul(g1[1], u1[1])); w.w = cvt_pk_bf16(silu_mul(g1[2], u1[2]), silu_mul(g1[3], u1[3]));
;                 *(u32x4*)rowp = w; }
	v_cvt_pk_bf16_f32 v106, v104, v105
	v_cvt_pk_bf16_f32 v104, v108, v109
	v_cvt_pk_bf16_f32 v105, v110, v111
	global_store_dwordx4 v[186:187], v[104:107], off
	v_exp_f32_e32 v102, v102
	v_fma_f32 v101, v101, v188, v188
	v_rcp_f32_e32 v101, v101
	v_mul_f32_e32 v103, v189, v103
	v_mul_f32_e32 v92, v92, v100
	v_exp_f32_e32 v103, v103
	v_fma_f32 v102, v102, v188, v188
	v_rcp_f32_e32 v102, v102
	v_mul_f32_e32 v96, v189, v96
	v_mul_f32_e32 v93, v93, v101
	v_exp_f32_e32 v96, v96
	v_fma_f32 v103, v103, v188, v188
	v_rcp_f32_e32 v103, v103
	v_mul_f32_e32 v97, v189, v97
	v_mul_f32_e32 v94, v94, v102
	v_exp_f32_e32 v97, v97
	v_fma_f32 v96, v96, v188, v188
	v_rcp_f32_e32 v96, v96
	v_mul_f32_e32 v98, v189, v98
	v_mul_f32_e32 v95, v95, v103
	v_exp_f32_e32 v98, v98
	v_fma_f32 v97, v97, v188, v188
	v_rcp_f32_e32 v97, v97
	v_mul_f32_e32 v99, v189, v99
	v_mul_f32_e32 v88, v88, v96
	v_exp_f32_e32 v99, v99
	v_fma_f32 v98, v98, v188, v188
	v_rcp_f32_e32 v98, v98
	v_mul_f32_e32 v84, v193, v84
	v_mul_f32_e32 v89, v89, v97
	v_exp_f32_e32 v84, v84
	v_fma_f32 v99, v99, v188, v188
	v_rcp_f32_e32 v99, v99
	v_mul_f32_e32 v85, v193, v85
	v_mul_f32_e32 v90, v90, v98
	v_exp_f32_e32 v85, v85
	v_fma_f32 v84, v84, v192, v192
	v_rcp_f32_e32 v84, v84
	v_mul_f32_e32 v86, v193, v86
	v_mul_f32_e32 v91, v91, v99
	v_cvt_pk_bf16_f32 v91, v90, v91
	v_cvt_pk_bf16_f32 v90, v88, v89
	v_cvt_pk_bf16_f32 v88, v92, v93
	v_cvt_pk_bf16_f32 v89, v94, v95
	global_store_dwordx4 v[190:191], v[88:91], off
	v_exp_f32_e32 v86, v86
	v_fma_f32 v85, v85, v192, v192
	v_rcp_f32_e32 v85, v85
	v_mul_f32_e32 v87, v193, v87
	v_mul_f32_e32 v70, v70, v84
	v_exp_f32_e32 v87, v87
	v_fma_f32 v86, v86, v192, v192
	v_rcp_f32_e32 v86, v86
	v_mul_f32_e32 v74, v193, v74
	v_mul_f32_e32 v71, v71, v85
	v_exp_f32_e32 v74, v74
	v_fma_f32 v87, v87, v192, v192
	v_rcp_f32_e32 v87, v87
	v_mul_f32_e32 v75, v193, v75
	v_mul_f32_e32 v72, v72, v86
	v_exp_f32_e32 v75, v75
	v_fma_f32 v74, v74, v192, v192
	v_rcp_f32_e32 v74, v74
	v_mul_f32_e32 v76, v193, v76
	v_mul_f32_e32 v73, v73, v87
	v_exp_f32_e32 v76, v76
	v_fma_f32 v75, v75, v192, v192
	v_rcp_f32_e32 v75, v75
	v_mul_f32_e32 v77, v193, v77
	v_mul_f32_e32 v66, v66, v74
	v_exp_f32_e32 v77, v77
	v_fma_f32 v76, v76, v192, v192
	v_rcp_f32_e32 v76, v76
	v_mul_f32_e32 v62, v199, v62
	v_mul_f32_e32 v67, v67, v75
	v_exp_f32_e32 v62, v62
	v_fma_f32 v77, v77, v192, v192
	v_rcp_f32_e32 v77, v77
	v_mul_f32_e32 v63, v199, v63
	v_mul_f32_e32 v68, v68, v76
	v_exp_f32_e32 v63, v63
	v_fma_f32 v62, v62, v198, v198
	v_rcp_f32_e32 v62, v62
	v_mul_f32_e32 v64, v199, v64
	v_mul_f32_e32 v69, v69, v77
	v_cvt_pk_bf16_f32 v69, v68, v69
	v_cvt_pk_bf16_f32 v68, v66, v67
	v_cvt_pk_bf16_f32 v66, v70, v71
	v_cvt_pk_bf16_f32 v67, v72, v73
	global_store_dwordx4 v[194:195], v[66:69], off
	v_exp_f32_e32 v64, v64
	v_fma_f32 v63, v63, v198, v198
	v_rcp_f32_e32 v63, v63
	v_mul_f32_e32 v65, v199, v65
	v_mul_f32_e32 v54, v54, v62
	v_exp_f32_e32 v65, v65
	v_fma_f32 v64, v64, v198, v198
	v_rcp_f32_e32 v64, v64
	v_mul_f32_e32 v58, v199, v58
	v_mul_f32_e32 v55, v55, v63
	v_exp_f32_e32 v58, v58
	v_fma_f32 v65, v65, v198, v198
	v_rcp_f32_e32 v65, v65
	v_mul_f32_e32 v59, v199, v59
	v_mul_f32_e32 v56, v56, v64
	v_exp_f32_e32 v59, v59
	v_fma_f32 v58, v58, v198, v198
	v_rcp_f32_e32 v58, v58
	v_mul_f32_e32 v60, v199, v60
	v_mul_f32_e32 v57, v57, v65
	v_exp_f32_e32 v60, v60
	v_fma_f32 v59, v59, v198, v198
	v_rcp_f32_e32 v59, v59
	v_mul_f32_e32 v61, v199, v61
	v_mul_f32_e32 v50, v50, v58
	v_exp_f32_e32 v61, v61
	v_fma_f32 v60, v60, v198, v198
	v_rcp_f32_e32 v60, v60
	v_mul_f32_e32 v46, v203, v46
	v_mul_f32_e32 v51, v51, v59
	v_exp_f32_e32 v46, v46
	v_fma_f32 v61, v61, v198, v198
	v_rcp_f32_e32 v61, v61
	v_mul_f32_e32 v47, v203, v47
	v_mul_f32_e32 v52, v52, v60
	v_exp_f32_e32 v47, v47
	v_fma_f32 v46, v46, v202, v202
	v_rcp_f32_e32 v46, v46
	v_mul_f32_e32 v48, v203, v48
	v_mul_f32_e32 v53, v53, v61
	v_cvt_pk_bf16_f32 v53, v52, v53
; __device__ __forceinline__ unsigned cvt_pk_bf16(float lo, float hi) { unsigned r; asm volatile("v_cvt_pk_bf16_f32 %0, %1, %2" : "=v"(r) : "v"(lo), "v"(hi)); return r; }
; __device__ __forceinline__ float silu_mul(float g, float u) { const float e = __builtin_amdgcn_exp2f(g * -1.4426950408889634f); return g * u * __builtin_amdgcn_rcpf(1.0f + e); }
; #define PG8_BAR __builtin_amdgcn_s_barrier()
;     __device__ __forceinline__ void operator()(const f32x4 (&acc)[2][2][4][2], const Unit& u, int wr, int wc, int fr, int fq) const {
;     ...
;         for (int ai = 0; ai < 2; ++ai)
; #pragma unroll
;             for (int m = 0; m < 4; ++m) { const int row = row0 + ai * HALF + m * 16; bf16_t* rowp = O + (size_t)row * ldc + col0; const float rs = rs8[ai][m];
;                 const f32x4 g0 = acc[ai][0][m][0] * rs, g1 = acc[ai][0][m][1] * rs, u0 = acc[ai][1][m][0] * rs, u1 = acc[ai][1][m][1] * rs;
;                 u32x4 w; w.x = cvt_pk_bf16(silu_mul(g0[0], u0[0]), silu_mul(g0[1], u0[1])); w.y = cvt_pk_bf16(silu_mul(g0[2], u0[2]), silu_mul(g0[3], u0[3]));
;                 w.z = cvt_pk_bf16(silu_mul(g1[0], u1[0]), silu_mul(g1[1], u1[1])); w.w = cvt_pk_bf16(silu_mul(g1[2], u1[2]), silu_mul(g1[3], u1[3]));
;                 *(u32x4*)rowp = w; }
; template <class Epi, class Sched, bool ALIGN_EPI = false, bool SP2 = false>
; __device__ __forceinline__ void gemm_phase(PG8_LAS unsigned char* lds, const Gemm g, const Sched& S, const Epi& E) {
;     ...
;         if (!has_next) break;
; #pragma unroll
;         for (int a = 0; a < 2; ++a)
; #pragma unroll
;             for (int b = 0; b < 2; ++b)
; #pragma unroll
;                 for (int m = 0; m < 4; ++m)
; #pragma unroll
;                     for (int n = 0; n < 2; ++n) acc[a][b][m][n] = (f32x4){0.f, 0.f, 0.f, 0.f};
;         cur = nxt; cA = nA; cB = nB; ++ui;
;         if constexpr (ALIGN_EPI) { if (wr == 1) PG8_BAR; }
	v_cvt_pk_bf16_f32 v52, v50, v51
	v_cvt_pk_bf16_f32 v50, v54, v55
	v_cvt_pk_bf16_f32 v51, v56, v57
	global_store_dwordx4 v[200:201], v[50:53], off
	v_exp_f32_e32 v48, v48
	v_fma_f32 v47, v47, v202, v202
	v_rcp_f32_e32 v47, v47
	v_mul_f32_e32 v49, v203, v49
	v_mul_f32_e32 v38, v38, v46
	v_exp_f32_e32 v49, v49
	v_fma_f32 v48, v48, v202, v202
	v_rcp_f32_e32 v48, v48
	v_mul_f32_e32 v42, v203, v42
	v_mul_f32_e32 v39, v39, v47
	v_exp_f32_e32 v42, v42
	v_fma_f32 v49, v49, v202, v202
	v_rcp_f32_e32 v49, v49
	v_mul_f32_e32 v43, v203, v43
	v_mul_f32_e32 v40, v40, v48
	v_exp_f32_e32 v43, v43
	v_fma_f32 v42, v42, v202, v202
	v_rcp_f32_e32 v42, v42
	v_mul_f32_e32 v44, v203, v44
	v_mul_f32_e32 v41, v41, v49
	v_exp_f32_e32 v44, v44
	v_fma_f32 v43, v43, v202, v202
	v_rcp_f32_e32 v43, v43
	v_mul_f32_e32 v45, v203, v45
	v_mul_f32_e32 v34, v34, v42
	v_exp_f32_e32 v45, v45
	v_fma_f32 v44, v44, v202, v202
	v_rcp_f32_e32 v44, v44
	v_mul_f32_e32 v30, v207, v30
	v_mul_f32_e32 v35, v35, v43
	v_exp_f32_e32 v30, v30
	v_fma_f32 v45, v45, v202, v202
	v_rcp_f32_e32 v45, v45
	v_mul_f32_e32 v31, v207, v31
	v_mul_f32_e32 v36, v36, v44
	v_exp_f32_e32 v31, v31
	v_fma_f32 v30, v30, v206, v206
	v_rcp_f32_e32 v30, v30
	v_mul_f32_e32 v32, v207, v32
	v_mul_f32_e32 v37, v37, v45
	v_cvt_pk_bf16_f32 v37, v36, v37
	v_cvt_pk_bf16_f32 v36, v34, v35
	v_cvt_pk_bf16_f32 v34, v38, v39
	v_cvt_pk_bf16_f32 v35, v40, v41
	global_store_dwordx4 v[204:205], v[34:37], off
	v_exp_f32_e32 v32, v32
	v_fma_f32 v31, v31, v206, v206
	v_rcp_f32_e32 v31, v31
	v_mul_f32_e32 v33, v207, v33
	v_mul_f32_e32 v22, v22, v30
	v_exp_f32_e32 v33, v33
	v_fma_f32 v32, v32, v206, v206
	v_rcp_f32_e32 v32, v32
	v_mul_f32_e32 v26, v207, v26
	v_mul_f32_e32 v23, v23, v31
	v_exp_f32_e32 v26, v26
	v_fma_f32 v33, v33, v206, v206
	v_rcp_f32_e32 v33, v33
	v_mul_f32_e32 v27, v207, v27
	v_mul_f32_e32 v24, v24, v32
	v_exp_f32_e32 v27, v27
	v_fma_f32 v26, v26, v206, v206
	v_rcp_f32_e32 v26, v26
	v_mul_f32_e32 v28, v207, v28
	v_mul_f32_e32 v25, v25, v33
	v_exp_f32_e32 v28, v28
	v_fma_f32 v27, v27, v206, v206
	v_rcp_f32_e32 v27, v27
	v_mul_f32_e32 v29, v207, v29
	v_mul_f32_e32 v18, v18, v26
	v_exp_f32_e32 v29, v29
	v_fma_f32 v28, v28, v206, v206
	v_rcp_f32_e32 v28, v28
	v_mul_f32_e32 v14, v211, v14
	v_mul_f32_e32 v19, v19, v27
	v_exp_f32_e32 v14, v14
	v_fma_f32 v29, v29, v206, v206
	v_rcp_f32_e32 v29, v29
	v_mul_f32_e32 v15, v211, v15
	v_mul_f32_e32 v20, v20, v28
	v_exp_f32_e32 v15, v15
	v_fma_f32 v14, v14, v210, v210
	v_rcp_f32_e32 v14, v14
	v_mul_f32_e32 v16, v211, v16
	v_mul_f32_e32 v21, v21, v29
	v_cvt_pk_bf16_f32 v21, v20, v21
	v_cvt_pk_bf16_f32 v20, v18, v19
	v_cvt_pk_bf16_f32 v18, v22, v23
	v_cvt_pk_bf16_f32 v19, v24, v25
	global_store_dwordx4 v[208:209], v[18:21], off
	v_exp_f32_e32 v16, v16
	v_fma_f32 v15, v15, v210, v210
	v_rcp_f32_e32 v15, v15
	v_mul_f32_e32 v17, v211, v17
	v_mul_f32_e32 v6, v6, v14
	v_exp_f32_e32 v17, v17
	v_fma_f32 v16, v16, v210, v210
	v_rcp_f32_e32 v16, v16
	v_mul_f32_e32 v10, v211, v10
	v_mul_f32_e32 v7, v7, v15
	v_exp_f32_e32 v10, v10
	v_fma_f32 v17, v17, v210, v210
	v_rcp_f32_e32 v17, v17
	v_mul_f32_e32 v11, v211, v11
	v_mul_f32_e32 v8, v8, v16
	v_exp_f32_e32 v11, v11
	v_fma_f32 v10, v10, v210, v210
	v_rcp_f32_e32 v10, v10
	v_mul_f32_e32 v12, v211, v12
	v_mul_f32_e32 v9, v9, v17
	v_exp_f32_e32 v12, v12
	v_fma_f32 v11, v11, v210, v210
	v_rcp_f32_e32 v11, v11
	v_mul_f32_e32 v13, v211, v13
	v_mul_f32_e32 v2, v2, v10
	v_exp_f32_e32 v13, v13
	v_fma_f32 v12, v12, v210, v210
	v_rcp_f32_e32 v12, v12
	v_mul_f32_e32 v3, v3, v11
	v_fma_f32 v13, v13, v210, v210
	v_rcp_f32_e32 v13, v13
	v_mul_f32_e32 v4, v4, v12
	v_mul_f32_e32 v5, v5, v13
	v_cvt_pk_bf16_f32 v5, v4, v5
	v_cvt_pk_bf16_f32 v4, v2, v3
	v_cvt_pk_bf16_f32 v2, v6, v7
	v_cvt_pk_bf16_f32 v3, v8, v9
	global_store_dwordx4 v[212:213], v[2:5], off
	s_cbranch_vccnz .LBB0_632
	s_andn2_b64 vcc, exec, s[6:7]
	s_cbranch_vccnz .LBB0_631
	s_barrier
	s_branch .LBB0_631
